# v12 + last SwiGLU epilogue of a phase touches next phase's first A/B K-tiles (lead time for the last-arriving workgroup)
# baseline (speedup 1.0000x reference)
; __device__ __forceinline__ unsigned cvt_pk_bf16(float lo, float hi) { unsigned r; asm volatile("v_cvt_pk_bf16_f32 %0, %1, %2" : "=v"(r) : "v"(lo), "v"(hi)); return r; }
;     __device__ __forceinline__ void operator()(const f32x4 (&acc)[2][2][4][2], const Unit& u, const Unit& nxt, bool has_next, int wr, int wc, int fr, int fq) const {
;     ...
;         for (int g = 0; g < 8; ++g) cur[g] = rowss[row0 + (g >> 2) * HALF + (g & 3) * 16];
;         if (has_next) {
; #pragma unroll
;             for (int g = 0; g < 8; ++g) warm[g] = rowss[nxt.pm * BM + wr * 64 + fr + (g >> 2) * HALF + (g & 3) * 16];
;         }
; #pragma unroll
;         for (int g = 0; g < 8; ++g) {
;             const int ai = g >> 2, m = g & 3;
;             const float rs = __builtin_amdgcn_rsqf(ss_val(cur[g]) * inv_k + eps), rsn = rs * -1.44269504089f, rs2 = rs * rs;
;             float h[8];
; #pragma unroll
;             for (int n = 0; n < 2; ++n)
; #pragma unroll
;                 for (int jp = 0; jp < 2; ++jp) {
;                     const f32x2v av = {acc[ai][0][m][n][2 * jp], acc[ai][0][m][n][2 * jp + 1]}, gv = {acc[ai][1][m][n][2 * jp], acc[ai][1][m][n][2 * jp + 1]};
;                     const f32x2v t = (av * gv) * rs2, y = gv * rsn;
;                     f32x2v ex; ex.x = __builtin_amdgcn_exp2f(y.x); ex.y = __builtin_amdgcn_exp2f(y.y);
;                     const f32x2v d = ex + 1.0f;
;                     f32x2v r; r.x = __builtin_amdgcn_rcpf(d.x); r.y = __builtin_amdgcn_rcpf(d.y);
;                     const f32x2v o = t * r;
;                     h[4 * n + 2 * jp] = o.x; h[4 * n + 2 * jp + 1] = o.y;
;                 }
;             u32x4 w; w.x = cvt_pk_bf16(h[0], h[1]); w.y = cvt_pk_bf16(h[2], h[3]); w.z = cvt_pk_bf16(h[4], h[5]); w.w = cvt_pk_bf16(h[6], h[7]);
;             *(u32x4*)(O + (size_t)(row0 + ai * HALF + m * 16) * ldc + col0) = w;
; template <int L>
; __device__ __forceinline__ void layer(const Args& a, LAS unsigned char* lds, const XcdBarrier& bar, int lo, int hi, int wave, int lane, int b, int r, int GS) {
;     ...
;         pg8::Gemm g{HB, (const bf16*)(wl + W2_OFF), SEQ, D, DFF}; pg8::GroupOrder S; S.init(SEQ, D, GS, r);
;         pg8::EpiResid E{nullptr, XN, rowss + (size_t)(3 * L + 1) * M, 0.5f, D};
;         pg8::gemm_phase<pg8::EpiResid, pg8::GroupOrder, true, true>(lds, g, S, E);
.LBB0_180:
	s_waitcnt vmcnt(0)
	s_cbranch_vccz .Lepf_skip_0
	v_mov_b32_e32 v232, s95
	v_lshlrev_b32_e32 v232, 3, v232
	v_add_u32_e32 v232, s97, v232
	v_lshl_add_u32 v232, v232, 6, v200
	v_lshrrev_b32_e32 v231, 1, v232
	v_min_u32_e32 v231, 0x3ff, v231
	v_mul_u32_u24_e32 v231, 0x1600, v231
	v_and_b32_e32 v232, 1, v232
	v_lshlrev_b32_e32 v232, 7, v232
	v_add_u32_e32 v232, v231, v232
	v_add_u32_e32 v232, 0x1300000, v232
	global_load_dword v231, v232, s[34:35]
	v_readlane_b32 s101, v230, 6
	s_nop 3
	s_mul_i32 s101, s101, 704
	s_add_u32 s101, s101, 0xa000000
	v_mov_b32_e32 v233, s97
	v_lshl_add_u32 v233, v233, 6, v200
	v_mov_b32_e32 v234, s95
	v_lshrrev_b32_e32 v235, 4, v234
	v_and_b32_e32 v234, 3, v234
	v_lshl_or_b32 v234, v235, 2, v234
	v_lshlrev_b32_e32 v234, 8, v234
	v_lshrrev_b32_e32 v235, 1, v233
	v_add_u32_e32 v234, v234, v235
	v_mul_u32_u24_e32 v234, 0x1600, v234
	v_and_b32_e32 v233, 1, v233
	v_lshlrev_b32_e32 v233, 7, v233
	v_add3_u32 v233, v234, v233, s101
	global_load_dword v235, v233, s[34:35]
.Lepf_skip_0:
	v_or_b32_e32 v185, 16, v168
	v_pk_mul_f32 v[124:125], v[124:125], v[116:117]
	v_cvt_f32_u32_e32 v172, v172
	v_cvt_f32_u32_e32 v173, v173
	v_fmamk_f32 v172, v173, 0x4f800000, v172
	v_fmamk_f32 v169, v172, 0x26800000, v180
	v_mov_b32_e32 v232, v169
	v_rsq_f32_e32 v186, v169
	v_pk_mul_f32 v[120:121], v[120:121], v[112:113]
	v_pk_mul_f32 v[126:127], v[126:127], v[118:119]
	v_pk_mul_f32 v[122:123], v[122:123], v[114:115]
	v_mul_f32_e32 v184, 0xbfb8aa3b, v186
	v_pk_mul_f32 v[116:117], v[116:117], v[184:185] op_sel_hi:[1,0]
	v_pk_mul_f32 v[112:113], v[112:113], v[184:185] op_sel_hi:[1,0]
	v_exp_f32_e32 v116, v116
	v_exp_f32_e32 v117, v117
	v_pk_mul_f32 v[118:119], v[118:119], v[184:185] op_sel_hi:[1,0]
	v_exp_f32_e32 v112, v112
	v_exp_f32_e32 v113, v113
	v_pk_mul_f32 v[114:115], v[114:115], v[184:185] op_sel_hi:[1,0]
	v_exp_f32_e32 v118, v118
	v_exp_f32_e32 v119, v119
	v_exp_f32_e32 v114, v114
	v_exp_f32_e32 v115, v115
	v_pk_fma_f32 v[116:117], v[116:117], v[232:233], v[232:233] op_sel_hi:[1,0,0]
	v_pk_fma_f32 v[112:113], v[112:113], v[232:233], v[232:233] op_sel_hi:[1,0,0]
	v_rcp_f32_e32 v116, v116
	v_rcp_f32_e32 v117, v117
	v_pk_fma_f32 v[118:119], v[118:119], v[232:233], v[232:233] op_sel_hi:[1,0,0]
	v_rcp_f32_e32 v112, v112
	v_rcp_f32_e32 v113, v113
	v_pk_fma_f32 v[114:115], v[114:115], v[232:233], v[232:233] op_sel_hi:[1,0,0]
	v_rcp_f32_e32 v118, v118
	v_rcp_f32_e32 v119, v119
	v_rcp_f32_e32 v114, v114
	v_rcp_f32_e32 v115, v115
	v_or_b32_e32 v187, 32, v168
	v_pk_mul_f32 v[116:117], v[124:125], v[116:117]
	v_pk_mul_f32 v[112:113], v[120:121], v[112:113]
	v_pk_mul_f32 v[118:119], v[126:127], v[118:119]
	v_pk_mul_f32 v[114:115], v[122:123], v[114:115]
	v_cvt_pk_bf16_f32 v116, v116, v117
	v_cvt_pk_bf16_f32 v117, v118, v119
	v_cvt_pk_bf16_f32 v118, v112, v113
	v_lshl_or_b32 v182, s70, 7, v176
	v_cvt_pk_bf16_f32 v119, v114, v115
	v_ashrrev_i32_e32 v183, 31, v182
	v_mov_b64_e32 v[112:113], s[24:25]
	v_cvt_f32_u32_e32 v170, v170
	v_cvt_f32_u32_e32 v171, v171
	v_fmamk_f32 v170, v171, 0x4f800000, v170
	v_fmamk_f32 v114, v170, 0x26800000, v180
	v_mov_b32_e32 v234, v114
	v_rsq_f32_e32 v122, v114
	v_mad_i64_i32 v[120:121], s[56:57], v168, s69, v[112:113]
	v_lshlrev_b64 v[114:115], 1, v[182:183]
	v_lshl_add_u64 v[120:121], v[120:121], 0, v[114:115]
	global_store_dwordx4 v[120:121], v[116:119], off
	v_pk_mul_f32 v[104:105], v[104:105], v[96:97]
	v_pk_mul_f32 v[108:109], v[108:109], v[100:101]
	v_mul_f32_e32 v116, 0xbfb8aa3b, v122
	v_pk_mul_f32 v[96:97], v[96:97], v[116:117] op_sel_hi:[1,0]
	v_pk_mul_f32 v[100:101], v[100:101], v[116:117] op_sel_hi:[1,0]
	v_pk_mul_f32 v[106:107], v[106:107], v[98:99]
	v_exp_f32_e32 v96, v96
	v_exp_f32_e32 v97, v97
	v_pk_mul_f32 v[98:99], v[98:99], v[116:117] op_sel_hi:[1,0]
	v_exp_f32_e32 v100, v100
	v_exp_f32_e32 v101, v101
	v_exp_f32_e32 v98, v98
	v_exp_f32_e32 v99, v99
	v_pk_fma_f32 v[96:97], v[96:97], v[234:235], v[234:235] op_sel_hi:[1,0,0]
	v_pk_fma_f32 v[100:101], v[100:101], v[234:235], v[234:235] op_sel_hi:[1,0,0]
	v_rcp_f32_e32 v96, v96
	v_rcp_f32_e32 v97, v97
	v_pk_fma_f32 v[98:99], v[98:99], v[234:235], v[234:235] op_sel_hi:[1,0,0]
	v_rcp_f32_e32 v100, v100
	v_rcp_f32_e32 v101, v101
	v_rcp_f32_e32 v98, v98
	v_rcp_f32_e32 v99, v99
	v_pk_mul_f32 v[104:105], v[104:105], v[96:97]
	v_pk_mul_f32 v[100:101], v[108:109], v[100:101]
	v_pk_mul_f32 v[106:107], v[106:107], v[98:99]
	v_pk_mul_f32 v[110:111], v[110:111], v[102:103]
	v_pk_mul_f32 v[102:103], v[102:103], v[116:117] op_sel_hi:[1,0]
	v_cvt_pk_bf16_f32 v96, v100, v101
	v_exp_f32_e32 v102, v102
	v_exp_f32_e32 v103, v103
	s_nop 0
	v_pk_fma_f32 v[102:103], v[102:103], v[234:235], v[234:235] op_sel_hi:[1,0,0]
	v_rcp_f32_e32 v102, v102
	v_rcp_f32_e32 v103, v103
	s_nop 0
	v_pk_mul_f32 v[102:103], v[110:111], v[102:103]
	v_cvt_f32_u32_e32 v166, v166
	v_cvt_f32_u32_e32 v167, v167
	v_fmamk_f32 v166, v167, 0x4f800000, v166
	v_fmamk_f32 v100, v166, 0x26800000, v180
	v_mov_b32_e32 v236, v100
	v_cvt_pk_bf16_f32 v97, v102, v103
	v_rsq_f32_e32 v102, v100
	v_mad_i64_i32 v[100:101], s[56:57], v185, s69, v[112:113]
	v_lshl_add_u64 v[100:101], v[100:101], 0, v[114:115]
	v_cvt_pk_bf16_f32 v98, v104, v105
	v_cvt_pk_bf16_f32 v99, v106, v107
	global_store_dwordx4 v[100:101], v[96:99], off
	v_pk_mul_f32 v[88:89], v[88:89], v[80:81]
	v_pk_mul_f32 v[92:93], v[92:93], v[84:85]
	v_mul_f32_e32 v96, 0xbfb8aa3b, v102
	v_pk_mul_f32 v[80:81], v[80:81], v[96:97] op_sel_hi:[1,0]
	v_pk_mul_f32 v[84:85], v[84:85], v[96:97] op_sel_hi:[1,0]
	v_pk_mul_f32 v[90:91], v[90:91], v[82:83]
	v_exp_f32_e32 v80, v80
	v_exp_f32_e32 v81, v81
	v_pk_mul_f32 v[82:83], v[82:83], v[96:97] op_sel_hi:[1,0]
; __device__ __forceinline__ unsigned cvt_pk_bf16(float lo, float hi) { unsigned r; asm volatile("v_cvt_pk_bf16_f32 %0, %1, %2" : "=v"(r) : "v"(lo), "v"(hi)); return r; }
; __device__ __forceinline__ float ss_val(u64 v) { return (float)v * (1.0f / 1099511627776.0f); }
;     __device__ __forceinline__ void operator()(const f32x4 (&acc)[2][2][4][2], const Unit& u, const Unit& nxt, bool has_next, int wr, int wc, int fr, int fq) const {
;     ...
;         for (int g = 0; g < 8; ++g) {
;             const int ai = g >> 2, m = g & 3;
;             const float rs = __builtin_amdgcn_rsqf(ss_val(cur[g]) * inv_k + eps), rsn = rs * -1.44269504089f, rs2 = rs * rs;
;             float h[8];
; #pragma unroll
;             for (int n = 0; n < 2; ++n)
; #pragma unroll
;                 for (int jp = 0; jp < 2; ++jp) {
;                     const f32x2v av = {acc[ai][0][m][n][2 * jp], acc[ai][0][m][n][2 * jp + 1]}, gv = {acc[ai][1][m][n][2 * jp], acc[ai][1][m][n][2 * jp + 1]};
;                     const f32x2v t = (av * gv) * rs2, y = gv * rsn;
;                     f32x2v ex; ex.x = __builtin_amdgcn_exp2f(y.x); ex.y = __builtin_amdgcn_exp2f(y.y);
;                     const f32x2v d = ex + 1.0f;
;                     f32x2v r; r.x = __builtin_amdgcn_rcpf(d.x); r.y = __builtin_amdgcn_rcpf(d.y);
;                     const f32x2v o = t * r;
;                     h[4 * n + 2 * jp] = o.x; h[4 * n + 2 * jp + 1] = o.y;
;                 }
;             u32x4 w; w.x = cvt_pk_bf16(h[0], h[1]); w.y = cvt_pk_bf16(h[2], h[3]); w.z = cvt_pk_bf16(h[4], h[5]); w.w = cvt_pk_bf16(h[6], h[7]);
;             *(u32x4*)(O + (size_t)(row0 + ai * HALF + m * 16) * ldc + col0) = w;
	v_exp_f32_e32 v84, v84
	v_exp_f32_e32 v85, v85
	v_exp_f32_e32 v82, v82
	v_exp_f32_e32 v83, v83
	v_pk_fma_f32 v[80:81], v[80:81], v[236:237], v[236:237] op_sel_hi:[1,0,0]
	v_pk_fma_f32 v[84:85], v[84:85], v[236:237], v[236:237] op_sel_hi:[1,0,0]
	v_rcp_f32_e32 v80, v80
	v_rcp_f32_e32 v81, v81
	v_pk_fma_f32 v[82:83], v[82:83], v[236:237], v[236:237] op_sel_hi:[1,0,0]
	v_rcp_f32_e32 v84, v84
	v_rcp_f32_e32 v85, v85
	v_rcp_f32_e32 v82, v82
	v_rcp_f32_e32 v83, v83
	v_pk_mul_f32 v[88:89], v[88:89], v[80:81]
	v_pk_mul_f32 v[84:85], v[92:93], v[84:85]
	v_pk_mul_f32 v[90:91], v[90:91], v[82:83]
	v_pk_mul_f32 v[94:95], v[94:95], v[86:87]
	v_pk_mul_f32 v[86:87], v[86:87], v[96:97] op_sel_hi:[1,0]
	v_cvt_pk_bf16_f32 v80, v84, v85
	v_exp_f32_e32 v86, v86
	v_exp_f32_e32 v87, v87
	s_nop 0
	v_pk_fma_f32 v[86:87], v[86:87], v[236:237], v[236:237] op_sel_hi:[1,0,0]
	v_rcp_f32_e32 v86, v86
	v_rcp_f32_e32 v87, v87
	s_nop 0
	v_pk_mul_f32 v[86:87], v[94:95], v[86:87]
	v_cvt_f32_u32_e32 v164, v164
	v_cvt_f32_u32_e32 v165, v165
	v_fmamk_f32 v164, v165, 0x4f800000, v164
	v_fmamk_f32 v84, v164, 0x26800000, v180
	v_mov_b32_e32 v238, v84
	v_cvt_pk_bf16_f32 v81, v86, v87
	v_rsq_f32_e32 v86, v84
	v_mad_i64_i32 v[84:85], s[56:57], v187, s69, v[112:113]
	v_lshl_add_u64 v[84:85], v[84:85], 0, v[114:115]
	v_cvt_pk_bf16_f32 v82, v88, v89
	v_cvt_pk_bf16_f32 v83, v90, v91
	global_store_dwordx4 v[84:85], v[80:83], off
	v_pk_mul_f32 v[72:73], v[72:73], v[64:65]
	v_pk_mul_f32 v[76:77], v[76:77], v[68:69]
	v_mul_f32_e32 v80, 0xbfb8aa3b, v86
	v_pk_mul_f32 v[64:65], v[64:65], v[80:81] op_sel_hi:[1,0]
	v_pk_mul_f32 v[68:69], v[68:69], v[80:81] op_sel_hi:[1,0]
	v_pk_mul_f32 v[74:75], v[74:75], v[66:67]
	v_exp_f32_e32 v64, v64
	v_exp_f32_e32 v65, v65
	v_pk_mul_f32 v[66:67], v[66:67], v[80:81] op_sel_hi:[1,0]
	v_exp_f32_e32 v68, v68
	v_exp_f32_e32 v69, v69
	v_exp_f32_e32 v66, v66
	v_exp_f32_e32 v67, v67
	v_pk_fma_f32 v[64:65], v[64:65], v[238:239], v[238:239] op_sel_hi:[1,0,0]
	v_pk_fma_f32 v[68:69], v[68:69], v[238:239], v[238:239] op_sel_hi:[1,0,0]
	v_rcp_f32_e32 v64, v64
	v_rcp_f32_e32 v65, v65
	v_pk_fma_f32 v[66:67], v[66:67], v[238:239], v[238:239] op_sel_hi:[1,0,0]
	v_rcp_f32_e32 v68, v68
	v_rcp_f32_e32 v69, v69
	v_rcp_f32_e32 v66, v66
	v_rcp_f32_e32 v67, v67
	v_pk_mul_f32 v[72:73], v[72:73], v[64:65]
	v_pk_mul_f32 v[68:69], v[76:77], v[68:69]
	v_pk_mul_f32 v[74:75], v[74:75], v[66:67]
	v_pk_mul_f32 v[78:79], v[78:79], v[70:71]
	v_pk_mul_f32 v[70:71], v[70:71], v[80:81] op_sel_hi:[1,0]
	v_cvt_pk_bf16_f32 v64, v68, v69
	v_exp_f32_e32 v70, v70
	v_exp_f32_e32 v71, v71
	s_nop 0
	v_pk_fma_f32 v[70:71], v[70:71], v[238:239], v[238:239] op_sel_hi:[1,0,0]
	v_rcp_f32_e32 v70, v70
	v_rcp_f32_e32 v71, v71
	s_nop 0
	v_pk_mul_f32 v[70:71], v[78:79], v[70:71]
	v_cvt_f32_u32_e32 v162, v162
	v_cvt_f32_u32_e32 v163, v163
	v_fmamk_f32 v162, v163, 0x4f800000, v162
	v_fmamk_f32 v68, v162, 0x26800000, v180
	v_mov_b32_e32 v240, v68
	v_cvt_pk_bf16_f32 v65, v70, v71
	v_rsq_f32_e32 v70, v68
	v_or_b32_e32 v188, 48, v168
	v_mad_i64_i32 v[68:69], s[56:57], v188, s69, v[112:113]
	v_lshl_add_u64 v[68:69], v[68:69], 0, v[114:115]
	v_cvt_pk_bf16_f32 v66, v72, v73
	v_cvt_pk_bf16_f32 v67, v74, v75
	global_store_dwordx4 v[68:69], v[64:67], off
	v_pk_mul_f32 v[56:57], v[56:57], v[48:49]
	v_pk_mul_f32 v[60:61], v[60:61], v[52:53]
	v_mul_f32_e32 v64, 0xbfb8aa3b, v70
	v_pk_mul_f32 v[48:49], v[48:49], v[64:65] op_sel_hi:[1,0]
	v_pk_mul_f32 v[52:53], v[52:53], v[64:65] op_sel_hi:[1,0]
	v_pk_mul_f32 v[58:59], v[58:59], v[50:51]
	v_exp_f32_e32 v48, v48
	v_exp_f32_e32 v49, v49
	v_pk_mul_f32 v[50:51], v[50:51], v[64:65] op_sel_hi:[1,0]
	v_exp_f32_e32 v52, v52
	v_exp_f32_e32 v53, v53
	v_exp_f32_e32 v50, v50
	v_exp_f32_e32 v51, v51
	v_pk_fma_f32 v[48:49], v[48:49], v[240:241], v[240:241] op_sel_hi:[1,0,0]
	v_pk_fma_f32 v[52:53], v[52:53], v[240:241], v[240:241] op_sel_hi:[1,0,0]
	v_rcp_f32_e32 v48, v48
	v_rcp_f32_e32 v49, v49
	v_pk_fma_f32 v[50:51], v[50:51], v[240:241], v[240:241] op_sel_hi:[1,0,0]
	v_rcp_f32_e32 v52, v52
	v_rcp_f32_e32 v53, v53
	v_rcp_f32_e32 v50, v50
	v_rcp_f32_e32 v51, v51
	v_pk_mul_f32 v[56:57], v[56:57], v[48:49]
	v_pk_mul_f32 v[52:53], v[60:61], v[52:53]
	v_pk_mul_f32 v[58:59], v[58:59], v[50:51]
	v_pk_mul_f32 v[62:63], v[62:63], v[54:55]
	v_pk_mul_f32 v[54:55], v[54:55], v[64:65] op_sel_hi:[1,0]
	v_cvt_pk_bf16_f32 v48, v52, v53
	v_exp_f32_e32 v54, v54
	v_exp_f32_e32 v55, v55
	s_nop 0
	v_pk_fma_f32 v[54:55], v[54:55], v[240:241], v[240:241] op_sel_hi:[1,0,0]
	v_rcp_f32_e32 v54, v54
	v_rcp_f32_e32 v55, v55
	s_nop 0
	v_pk_mul_f32 v[54:55], v[62:63], v[54:55]
	v_cvt_f32_u32_e32 v160, v160
	v_cvt_f32_u32_e32 v161, v161
	v_fmamk_f32 v160, v161, 0x4f800000, v160
	v_fmamk_f32 v52, v160, 0x26800000, v180
	v_mov_b32_e32 v242, v52
	v_cvt_pk_bf16_f32 v49, v54, v55
	v_rsq_f32_e32 v54, v52
	v_add_u32_e32 v181, 0x80, v168
	v_mad_i64_i32 v[52:53], s[56:57], v181, s69, v[112:113]
	v_lshl_add_u64 v[52:53], v[52:53], 0, v[114:115]
	v_cvt_pk_bf16_f32 v50, v56, v57
	v_cvt_pk_bf16_f32 v51, v58, v59
	global_store_dwordx4 v[52:53], v[48:51], off
	v_pk_mul_f32 v[40:41], v[40:41], v[32:33]
	v_pk_mul_f32 v[44:45], v[44:45], v[36:37]
	v_mul_f32_e32 v48, 0xbfb8aa3b, v54
	v_pk_mul_f32 v[32:33], v[32:33], v[48:49] op_sel_hi:[1,0]
	v_pk_mul_f32 v[36:37], v[36:37], v[48:49] op_sel_hi:[1,0]
	v_pk_mul_f32 v[42:43], v[42:43], v[34:35]
; __device__ __forceinline__ unsigned cvt_pk_bf16(float lo, float hi) { unsigned r; asm volatile("v_cvt_pk_bf16_f32 %0, %1, %2" : "=v"(r) : "v"(lo), "v"(hi)); return r; }
; __device__ __forceinline__ float ss_val(u64 v) { return (float)v * (1.0f / 1099511627776.0f); }
;     __device__ __forceinline__ void operator()(const f32x4 (&acc)[2][2][4][2], const Unit& u, const Unit& nxt, bool has_next, int wr, int wc, int fr, int fq) const {
;     ...
; #pragma unroll
;         for (int g = 0; g < 8; ++g) {
;             const int ai = g >> 2, m = g & 3;
;             const float rs = __builtin_amdgcn_rsqf(ss_val(cur[g]) * inv_k + eps), rsn = rs * -1.44269504089f, rs2 = rs * rs;
;             float h[8];
; #pragma unroll
;             for (int n = 0; n < 2; ++n)
; #pragma unroll
;                 for (int jp = 0; jp < 2; ++jp) {
;                     const f32x2v av = {acc[ai][0][m][n][2 * jp], acc[ai][0][m][n][2 * jp + 1]}, gv = {acc[ai][1][m][n][2 * jp], acc[ai][1][m][n][2 * jp + 1]};
;                     const f32x2v t = (av * gv) * rs2, y = gv * rsn;
;                     f32x2v ex; ex.x = __builtin_amdgcn_exp2f(y.x); ex.y = __builtin_amdgcn_exp2f(y.y);
;                     const f32x2v d = ex + 1.0f;
;                     f32x2v r; r.x = __builtin_amdgcn_rcpf(d.x); r.y = __builtin_amdgcn_rcpf(d.y);
;                     const f32x2v o = t * r;
;                     h[4 * n + 2 * jp] = o.x; h[4 * n + 2 * jp + 1] = o.y;
;                 }
;             u32x4 w; w.x = cvt_pk_bf16(h[0], h[1]); w.y = cvt_pk_bf16(h[2], h[3]); w.z = cvt_pk_bf16(h[4], h[5]); w.w = cvt_pk_bf16(h[6], h[7]);
;             *(u32x4*)(O + (size_t)(row0 + ai * HALF + m * 16) * ldc + col0) = w;
;         }
;         if (has_next) { u64 x = 0;
; #pragma unroll
;             for (int g = 0; g < 8; ++g) x |= warm[g];
;             asm volatile("" :: "v"((unsigned)x), "v"((unsigned)(x >> 32))); }
	v_exp_f32_e32 v32, v32
	v_exp_f32_e32 v33, v33
	v_pk_mul_f32 v[34:35], v[34:35], v[48:49] op_sel_hi:[1,0]
	v_exp_f32_e32 v36, v36
	v_exp_f32_e32 v37, v37
	v_exp_f32_e32 v34, v34
	v_exp_f32_e32 v35, v35
	v_pk_fma_f32 v[32:33], v[32:33], v[242:243], v[242:243] op_sel_hi:[1,0,0]
	v_pk_fma_f32 v[36:37], v[36:37], v[242:243], v[242:243] op_sel_hi:[1,0,0]
	v_rcp_f32_e32 v32, v32
	v_rcp_f32_e32 v33, v33
	v_pk_fma_f32 v[34:35], v[34:35], v[242:243], v[242:243] op_sel_hi:[1,0,0]
	v_rcp_f32_e32 v36, v36
	v_rcp_f32_e32 v37, v37
	v_rcp_f32_e32 v34, v34
	v_rcp_f32_e32 v35, v35
	v_pk_mul_f32 v[40:41], v[40:41], v[32:33]
	v_pk_mul_f32 v[36:37], v[44:45], v[36:37]
	v_pk_mul_f32 v[42:43], v[42:43], v[34:35]
	v_pk_mul_f32 v[46:47], v[46:47], v[38:39]
	v_pk_mul_f32 v[38:39], v[38:39], v[48:49] op_sel_hi:[1,0]
	v_cvt_pk_bf16_f32 v32, v36, v37
	v_exp_f32_e32 v38, v38
	v_exp_f32_e32 v39, v39
	s_nop 0
	v_pk_fma_f32 v[38:39], v[38:39], v[242:243], v[242:243] op_sel_hi:[1,0,0]
	v_rcp_f32_e32 v38, v38
	v_rcp_f32_e32 v39, v39
	s_nop 0
	v_pk_mul_f32 v[38:39], v[46:47], v[38:39]
	v_cvt_f32_u32_e32 v158, v158
	v_cvt_f32_u32_e32 v159, v159
	v_fmamk_f32 v158, v159, 0x4f800000, v158
	v_fmamk_f32 v36, v158, 0x26800000, v180
	v_mov_b32_e32 v244, v36
	v_cvt_pk_bf16_f32 v33, v38, v39
	v_rsq_f32_e32 v38, v36
	v_add_u32_e32 v173, 0x90, v168
	v_mad_i64_i32 v[36:37], s[56:57], v173, s69, v[112:113]
	v_lshl_add_u64 v[36:37], v[36:37], 0, v[114:115]
	v_cvt_pk_bf16_f32 v34, v40, v41
	v_cvt_pk_bf16_f32 v35, v42, v43
	global_store_dwordx4 v[36:37], v[32:35], off
	v_pk_mul_f32 v[24:25], v[24:25], v[16:17]
	v_pk_mul_f32 v[28:29], v[28:29], v[20:21]
	v_mul_f32_e32 v32, 0xbfb8aa3b, v38
	v_pk_mul_f32 v[16:17], v[16:17], v[32:33] op_sel_hi:[1,0]
	v_pk_mul_f32 v[20:21], v[20:21], v[32:33] op_sel_hi:[1,0]
	v_pk_mul_f32 v[26:27], v[26:27], v[18:19]
	v_exp_f32_e32 v16, v16
	v_exp_f32_e32 v17, v17
	v_pk_mul_f32 v[18:19], v[18:19], v[32:33] op_sel_hi:[1,0]
	v_exp_f32_e32 v20, v20
	v_exp_f32_e32 v21, v21
	v_exp_f32_e32 v18, v18
	v_exp_f32_e32 v19, v19
	v_pk_fma_f32 v[16:17], v[16:17], v[244:245], v[244:245] op_sel_hi:[1,0,0]
	v_pk_fma_f32 v[20:21], v[20:21], v[244:245], v[244:245] op_sel_hi:[1,0,0]
	v_rcp_f32_e32 v16, v16
	v_rcp_f32_e32 v17, v17
	v_pk_fma_f32 v[18:19], v[18:19], v[244:245], v[244:245] op_sel_hi:[1,0,0]
	v_rcp_f32_e32 v20, v20
	v_rcp_f32_e32 v21, v21
	v_rcp_f32_e32 v18, v18
	v_rcp_f32_e32 v19, v19
	v_pk_mul_f32 v[24:25], v[24:25], v[16:17]
	v_pk_mul_f32 v[20:21], v[28:29], v[20:21]
	v_pk_mul_f32 v[26:27], v[26:27], v[18:19]
	v_pk_mul_f32 v[30:31], v[30:31], v[22:23]
	v_pk_mul_f32 v[22:23], v[22:23], v[32:33] op_sel_hi:[1,0]
	v_cvt_pk_bf16_f32 v16, v20, v21
	v_exp_f32_e32 v22, v22
	v_exp_f32_e32 v23, v23
	s_nop 0
	v_pk_fma_f32 v[22:23], v[22:23], v[244:245], v[244:245] op_sel_hi:[1,0,0]
	v_rcp_f32_e32 v22, v22
	v_rcp_f32_e32 v23, v23
	s_nop 0
	v_pk_mul_f32 v[22:23], v[30:31], v[22:23]
	v_cvt_f32_u32_e32 v156, v156
	v_cvt_f32_u32_e32 v157, v157
	v_fmamk_f32 v156, v157, 0x4f800000, v156
	v_fmamk_f32 v20, v156, 0x26800000, v180
	v_mov_b32_e32 v246, v20
	v_cvt_pk_bf16_f32 v17, v22, v23
	v_rsq_f32_e32 v22, v20
	v_add_u32_e32 v172, 0xa0, v168
	v_mad_i64_i32 v[20:21], s[56:57], v172, s69, v[112:113]
	v_lshl_add_u64 v[20:21], v[20:21], 0, v[114:115]
	v_cvt_pk_bf16_f32 v18, v24, v25
	v_cvt_pk_bf16_f32 v19, v26, v27
	global_store_dwordx4 v[20:21], v[16:19], off
	v_pk_mul_f32 v[12:13], v[12:13], v[4:5]
	v_pk_mul_f32 v[8:9], v[8:9], v[0:1]
	v_mul_f32_e32 v16, 0xbfb8aa3b, v22
	v_pk_mul_f32 v[4:5], v[4:5], v[16:17] op_sel_hi:[1,0]
	v_pk_mul_f32 v[0:1], v[0:1], v[16:17] op_sel_hi:[1,0]
	v_exp_f32_e32 v4, v4
	v_exp_f32_e32 v5, v5
	v_pk_mul_f32 v[10:11], v[10:11], v[2:3]
	v_exp_f32_e32 v0, v0
	v_exp_f32_e32 v1, v1
	v_pk_mul_f32 v[2:3], v[2:3], v[16:17] op_sel_hi:[1,0]
	v_pk_mul_f32 v[14:15], v[14:15], v[6:7]
	v_exp_f32_e32 v2, v2
	v_exp_f32_e32 v3, v3
	v_pk_mul_f32 v[6:7], v[6:7], v[16:17] op_sel_hi:[1,0]
	v_pk_fma_f32 v[4:5], v[4:5], v[246:247], v[246:247] op_sel_hi:[1,0,0]
	v_exp_f32_e32 v6, v6
	v_exp_f32_e32 v7, v7
	v_pk_fma_f32 v[0:1], v[0:1], v[246:247], v[246:247] op_sel_hi:[1,0,0]
	v_rcp_f32_e32 v4, v4
	v_rcp_f32_e32 v5, v5
	v_rcp_f32_e32 v0, v0
	v_rcp_f32_e32 v1, v1
	v_pk_fma_f32 v[2:3], v[2:3], v[246:247], v[246:247] op_sel_hi:[1,0,0]
	v_rcp_f32_e32 v2, v2
	v_rcp_f32_e32 v3, v3
	v_pk_fma_f32 v[6:7], v[6:7], v[246:247], v[246:247] op_sel_hi:[1,0,0]
	v_rcp_f32_e32 v6, v6
	v_rcp_f32_e32 v7, v7
	v_add_u32_e32 v169, 0xb0, v168
	v_pk_mul_f32 v[4:5], v[12:13], v[4:5]
	v_pk_mul_f32 v[8:9], v[8:9], v[0:1]
	v_pk_mul_f32 v[10:11], v[10:11], v[2:3]
	v_cvt_pk_bf16_f32 v0, v4, v5
	v_mad_i64_i32 v[4:5], s[56:57], v169, s69, v[112:113]
	v_lshl_add_u64 v[4:5], v[4:5], 0, v[114:115]
	s_and_b64 vcc, exec, s[2:3]
	s_mov_b64 s[2:3], -1
	v_pk_mul_f32 v[6:7], v[14:15], v[6:7]
	s_nop 0
	v_cvt_pk_bf16_f32 v1, v6, v7
	v_cvt_pk_bf16_f32 v2, v8, v9
	v_cvt_pk_bf16_f32 v3, v10, v11
	global_store_dwordx4 v[4:5], v[0:3], off
	s_cbranch_vccnz .LBB0_171
	s_nop 0
	v_or_b32_e32 v0, v155, v153
	v_or_b32_e32 v1, v154, v152
	v_or3_b32 v0, v0, v149, v151
	v_or3_b32 v1, v1, v148, v150
	v_or3_b32 v0, v0, v145, v147
	v_or3_b32 v1, v1, v144, v146
	s_andn2_b64 vcc, exec, s[4:5]
	v_or3_b32 v0, v0, v141, v143
	v_or3_b32 v1, v1, v140, v142
	s_cbranch_vccnz .LBB0_170
	s_barrier
	s_branch .LBB0_170

; __device__ __forceinline__ unsigned cvt_pk_bf16(float lo, float hi) { unsigned r; asm volatile("v_cvt_pk_bf16_f32 %0, %1, %2" : "=v"(r) : "v"(lo), "v"(hi)); return r; }
; __device__ __forceinline__ float ss_val(u64 v) { return (float)v * (1.0f / 1099511627776.0f); }
;     __device__ __forceinline__ void operator()(const f32x4 (&acc)[2][2][4][2], const Unit& u, const Unit& nxt, bool has_next, int wr, int wc, int fr, int fq) const {
;         const int row0 = u.pm * BM + wr * 64 + fr, col0 = u.pn * HALF + wc * 32 + 8 * fq;
;         u64 cur[8], warm[8];
; #pragma unroll
;         for (int g = 0; g < 8; ++g) cur[g] = rowss[row0 + (g >> 2) * HALF + (g & 3) * 16];
;         if (has_next) {
; #pragma unroll
;             for (int g = 0; g < 8; ++g) warm[g] = rowss[nxt.pm * BM + wr * 64 + fr + (g >> 2) * HALF + (g & 3) * 16];
;         }
; #pragma unroll
;         for (int g = 0; g < 8; ++g) {
;             const int ai = g >> 2, m = g & 3;
;             const float rs = __builtin_amdgcn_rsqf(ss_val(cur[g]) * inv_k + eps), rsn = rs * -1.44269504089f, rs2 = rs * rs;
;             float h[8];
; #pragma unroll
;             for (int n = 0; n < 2; ++n)
; #pragma unroll
;                 for (int jp = 0; jp < 2; ++jp) {
;                     const f32x2v av = {acc[ai][0][m][n][2 * jp], acc[ai][0][m][n][2 * jp + 1]}, gv = {acc[ai][1][m][n][2 * jp], acc[ai][1][m][n][2 * jp + 1]};
;                     const f32x2v t = (av * gv) * rs2, y = gv * rsn;
;                     f32x2v ex; ex.x = __builtin_amdgcn_exp2f(y.x); ex.y = __builtin_amdgcn_exp2f(y.y);
;                     const f32x2v d = ex + 1.0f;
;                     f32x2v r; r.x = __builtin_amdgcn_rcpf(d.x); r.y = __builtin_amdgcn_rcpf(d.y);
;                     const f32x2v o = t * r;
;                     h[4 * n + 2 * jp] = o.x; h[4 * n + 2 * jp + 1] = o.y;
;                 }
;             u32x4 w; w.x = cvt_pk_bf16(h[0], h[1]); w.y = cvt_pk_bf16(h[2], h[3]); w.z = cvt_pk_bf16(h[4], h[5]); w.w = cvt_pk_bf16(h[6], h[7]);
;             *(u32x4*)(O + (size_t)(row0 + ai * HALF + m * 16) * ldc + col0) = w;
;         }
.LBB0_665:
	s_waitcnt vmcnt(0)
	s_cbranch_vccz .Lepf_skip_1
	v_mov_b32_e32 v232, s95
	v_lshlrev_b32_e32 v232, 3, v232
	v_add_u32_e32 v232, s97, v232
	v_lshl_add_u32 v232, v232, 6, v200
	v_lshrrev_b32_e32 v231, 1, v232
	v_min_u32_e32 v231, 0x3ff, v231
	v_mul_u32_u24_e32 v231, 0x1600, v231
	v_and_b32_e32 v232, 1, v232
	v_lshlrev_b32_e32 v232, 7, v232
	v_add_u32_e32 v232, v231, v232
	v_add_u32_e32 v232, 0x2b00000, v232
	global_load_dword v231, v232, s[34:35]
	v_readlane_b32 s101, v230, 6
	s_nop 3
	s_mul_i32 s101, s101, 704
	s_add_u32 s101, s101, 0xa000000
	v_mov_b32_e32 v233, s97
	v_lshl_add_u32 v233, v233, 6, v200
	v_mov_b32_e32 v234, s95
	v_lshrrev_b32_e32 v235, 4, v234
	v_and_b32_e32 v234, 3, v234
	v_lshl_or_b32 v234, v235, 2, v234
	v_lshlrev_b32_e32 v234, 8, v234
	v_lshrrev_b32_e32 v235, 1, v233
	v_add_u32_e32 v234, v234, v235
	v_mul_u32_u24_e32 v234, 0x1600, v234
	v_and_b32_e32 v233, 1, v233
	v_lshlrev_b32_e32 v233, 7, v233
	v_add3_u32 v233, v234, v233, s101
	global_load_dword v235, v233, s[34:35]
.Lepf_skip_1:
	v_pk_mul_f32 v[124:125], v[124:125], v[116:117]
	v_pk_mul_f32 v[120:121], v[120:121], v[112:113]
	v_cvt_f32_u32_e32 v186, v186
	v_cvt_f32_u32_e32 v187, v187
	v_fmamk_f32 v186, v187, 0x4f800000, v186
	v_fmamk_f32 v161, v186, 0x26800000, v193
	v_mov_b32_e32 v232, v161
	v_rsq_f32_e32 v161, v161
	v_pk_mul_f32 v[126:127], v[126:127], v[118:119]
	v_pk_mul_f32 v[122:123], v[122:123], v[114:115]
	v_lshl_or_b32 v186, s86, 7, v189
	v_mul_f32_e32 v194, 0xbfb8aa3b, v161
	v_pk_mul_f32 v[116:117], v[116:117], v[194:195] op_sel_hi:[1,0]
	v_pk_mul_f32 v[112:113], v[112:113], v[194:195] op_sel_hi:[1,0]
	v_exp_f32_e32 v116, v116
	v_exp_f32_e32 v117, v117
	v_pk_mul_f32 v[118:119], v[118:119], v[194:195] op_sel_hi:[1,0]
	v_exp_f32_e32 v112, v112
	v_exp_f32_e32 v113, v113
	v_pk_mul_f32 v[114:115], v[114:115], v[194:195] op_sel_hi:[1,0]
	v_exp_f32_e32 v118, v118
	v_exp_f32_e32 v119, v119
	v_exp_f32_e32 v114, v114
	v_exp_f32_e32 v115, v115
	v_pk_fma_f32 v[116:117], v[116:117], v[232:233], v[232:233] op_sel_hi:[1,0,0]
	v_pk_fma_f32 v[112:113], v[112:113], v[232:233], v[232:233] op_sel_hi:[1,0,0]
	v_rcp_f32_e32 v116, v116
	v_rcp_f32_e32 v117, v117
	v_pk_fma_f32 v[118:119], v[118:119], v[232:233], v[232:233] op_sel_hi:[1,0,0]
	v_rcp_f32_e32 v112, v112
	v_rcp_f32_e32 v113, v113
	v_pk_fma_f32 v[114:115], v[114:115], v[232:233], v[232:233] op_sel_hi:[1,0,0]
	v_rcp_f32_e32 v118, v118
	v_rcp_f32_e32 v119, v119
	v_rcp_f32_e32 v114, v114
	v_rcp_f32_e32 v115, v115
	v_pk_mul_f32 v[116:117], v[124:125], v[116:117]
	v_pk_mul_f32 v[112:113], v[120:121], v[112:113]
	v_pk_mul_f32 v[118:119], v[126:127], v[118:119]
	v_pk_mul_f32 v[114:115], v[122:123], v[114:115]
	v_cvt_pk_bf16_f32 v116, v116, v117
	v_cvt_pk_bf16_f32 v117, v118, v119
	v_cvt_pk_bf16_f32 v118, v112, v113
	v_ashrrev_i32_e32 v187, 31, v186
	v_cvt_pk_bf16_f32 v119, v114, v115
	v_mov_b64_e32 v[112:113], s[24:25]
	v_mad_i64_i32 v[120:121], s[58:59], v182, s57, v[112:113]
	v_cvt_f32_u32_e32 v184, v184
	v_cvt_f32_u32_e32 v185, v185
	v_fmamk_f32 v184, v185, 0x4f800000, v184
	v_fmamk_f32 v114, v184, 0x26800000, v193
	v_mov_b32_e32 v234, v114
	v_rsq_f32_e32 v122, v114
	v_lshlrev_b64 v[114:115], 1, v[186:187]
	v_lshl_add_u64 v[120:121], v[120:121], 0, v[114:115]
	global_store_dwordx4 v[120:121], v[116:119], off
	v_pk_mul_f32 v[104:105], v[104:105], v[96:97]
	v_pk_mul_f32 v[108:109], v[108:109], v[100:101]
	v_mul_f32_e32 v116, 0xbfb8aa3b, v122
	v_pk_mul_f32 v[96:97], v[96:97], v[116:117] op_sel_hi:[1,0]
	v_pk_mul_f32 v[100:101], v[100:101], v[116:117] op_sel_hi:[1,0]
	v_pk_mul_f32 v[106:107], v[106:107], v[98:99]
	v_exp_f32_e32 v96, v96
	v_exp_f32_e32 v97, v97
	v_pk_mul_f32 v[98:99], v[98:99], v[116:117] op_sel_hi:[1,0]
	v_exp_f32_e32 v100, v100
	v_exp_f32_e32 v101, v101
	v_exp_f32_e32 v98, v98
	v_exp_f32_e32 v99, v99
	v_pk_fma_f32 v[96:97], v[96:97], v[234:235], v[234:235] op_sel_hi:[1,0,0]
	v_pk_fma_f32 v[100:101], v[100:101], v[234:235], v[234:235] op_sel_hi:[1,0,0]
	v_rcp_f32_e32 v96, v96
	v_rcp_f32_e32 v97, v97
	v_pk_fma_f32 v[98:99], v[98:99], v[234:235], v[234:235] op_sel_hi:[1,0,0]
	v_rcp_f32_e32 v100, v100
	v_rcp_f32_e32 v101, v101
	v_rcp_f32_e32 v98, v98
	v_rcp_f32_e32 v99, v99
	v_pk_mul_f32 v[104:105], v[104:105], v[96:97]
	v_pk_mul_f32 v[100:101], v[108:109], v[100:101]
	v_pk_mul_f32 v[106:107], v[106:107], v[98:99]
	v_pk_mul_f32 v[110:111], v[110:111], v[102:103]
	v_pk_mul_f32 v[102:103], v[102:103], v[116:117] op_sel_hi:[1,0]
	v_cvt_pk_bf16_f32 v96, v100, v101
	v_exp_f32_e32 v102, v102
	v_exp_f32_e32 v103, v103
	s_nop 0
	v_pk_fma_f32 v[102:103], v[102:103], v[234:235], v[234:235] op_sel_hi:[1,0,0]
	v_rcp_f32_e32 v102, v102
	v_rcp_f32_e32 v103, v103
	s_nop 0
	v_pk_mul_f32 v[102:103], v[110:111], v[102:103]
	v_cvt_f32_u32_e32 v180, v180
	v_cvt_f32_u32_e32 v181, v181
	v_fmamk_f32 v180, v181, 0x4f800000, v180
	v_fmamk_f32 v100, v180, 0x26800000, v193
	v_mov_b32_e32 v236, v100
	v_cvt_pk_bf16_f32 v97, v102, v103
	v_rsq_f32_e32 v102, v100
	v_mad_i64_i32 v[100:101], s[58:59], v178, s57, v[112:113]
	v_lshl_add_u64 v[100:101], v[100:101], 0, v[114:115]
	v_cvt_pk_bf16_f32 v98, v104, v105
	v_cvt_pk_bf16_f32 v99, v106, v107
	global_store_dwordx4 v[100:101], v[96:99], off
	v_pk_mul_f32 v[88:89], v[88:89], v[80:81]
	v_pk_mul_f32 v[92:93], v[92:93], v[84:85]
	v_mul_f32_e32 v96, 0xbfb8aa3b, v102
	v_pk_mul_f32 v[80:81], v[80:81], v[96:97] op_sel_hi:[1,0]
	v_pk_mul_f32 v[84:85], v[84:85], v[96:97] op_sel_hi:[1,0]
	v_pk_mul_f32 v[90:91], v[90:91], v[82:83]
	v_exp_f32_e32 v80, v80
	v_exp_f32_e32 v81, v81
	v_pk_mul_f32 v[82:83], v[82:83], v[96:97] op_sel_hi:[1,0]
	v_exp_f32_e32 v84, v84
	v_exp_f32_e32 v85, v85
; __device__ __forceinline__ unsigned cvt_pk_bf16(float lo, float hi) { unsigned r; asm volatile("v_cvt_pk_bf16_f32 %0, %1, %2" : "=v"(r) : "v"(lo), "v"(hi)); return r; }
; __device__ __forceinline__ float ss_val(u64 v) { return (float)v * (1.0f / 1099511627776.0f); }
;     __device__ __forceinline__ void operator()(const f32x4 (&acc)[2][2][4][2], const Unit& u, const Unit& nxt, bool has_next, int wr, int wc, int fr, int fq) const {
;     ...
;         for (int g = 0; g < 8; ++g) {
;             const int ai = g >> 2, m = g & 3;
;             const float rs = __builtin_amdgcn_rsqf(ss_val(cur[g]) * inv_k + eps), rsn = rs * -1.44269504089f, rs2 = rs * rs;
;             float h[8];
; #pragma unroll
;             for (int n = 0; n < 2; ++n)
; #pragma unroll
;                 for (int jp = 0; jp < 2; ++jp) {
;                     const f32x2v av = {acc[ai][0][m][n][2 * jp], acc[ai][0][m][n][2 * jp + 1]}, gv = {acc[ai][1][m][n][2 * jp], acc[ai][1][m][n][2 * jp + 1]};
;                     const f32x2v t = (av * gv) * rs2, y = gv * rsn;
;                     f32x2v ex; ex.x = __builtin_amdgcn_exp2f(y.x); ex.y = __builtin_amdgcn_exp2f(y.y);
;                     const f32x2v d = ex + 1.0f;
;                     f32x2v r; r.x = __builtin_amdgcn_rcpf(d.x); r.y = __builtin_amdgcn_rcpf(d.y);
;                     const f32x2v o = t * r;
;                     h[4 * n + 2 * jp] = o.x; h[4 * n + 2 * jp + 1] = o.y;
;                 }
;             u32x4 w; w.x = cvt_pk_bf16(h[0], h[1]); w.y = cvt_pk_bf16(h[2], h[3]); w.z = cvt_pk_bf16(h[4], h[5]); w.w = cvt_pk_bf16(h[6], h[7]);
;             *(u32x4*)(O + (size_t)(row0 + ai * HALF + m * 16) * ldc + col0) = w;
;         }
	v_exp_f32_e32 v82, v82
	v_exp_f32_e32 v83, v83
	v_pk_fma_f32 v[80:81], v[80:81], v[236:237], v[236:237] op_sel_hi:[1,0,0]
	v_pk_fma_f32 v[84:85], v[84:85], v[236:237], v[236:237] op_sel_hi:[1,0,0]
	v_rcp_f32_e32 v80, v80
	v_rcp_f32_e32 v81, v81
	v_pk_fma_f32 v[82:83], v[82:83], v[236:237], v[236:237] op_sel_hi:[1,0,0]
	v_rcp_f32_e32 v84, v84
	v_rcp_f32_e32 v85, v85
	v_rcp_f32_e32 v82, v82
	v_rcp_f32_e32 v83, v83
	v_pk_mul_f32 v[88:89], v[88:89], v[80:81]
	v_pk_mul_f32 v[84:85], v[92:93], v[84:85]
	v_pk_mul_f32 v[90:91], v[90:91], v[82:83]
	v_pk_mul_f32 v[94:95], v[94:95], v[86:87]
	v_pk_mul_f32 v[86:87], v[86:87], v[96:97] op_sel_hi:[1,0]
	v_cvt_pk_bf16_f32 v80, v84, v85
	v_exp_f32_e32 v86, v86
	v_exp_f32_e32 v87, v87
	s_nop 0
	v_pk_fma_f32 v[86:87], v[86:87], v[236:237], v[236:237] op_sel_hi:[1,0,0]
	v_rcp_f32_e32 v86, v86
	v_rcp_f32_e32 v87, v87
	s_nop 0
	v_pk_mul_f32 v[86:87], v[94:95], v[86:87]
	v_cvt_f32_u32_e32 v176, v176
	v_cvt_f32_u32_e32 v177, v177
	v_fmamk_f32 v176, v177, 0x4f800000, v176
	v_fmamk_f32 v84, v176, 0x26800000, v193
	v_mov_b32_e32 v238, v84
	v_cvt_pk_bf16_f32 v81, v86, v87
	v_rsq_f32_e32 v86, v84
	v_mad_i64_i32 v[84:85], s[58:59], v174, s57, v[112:113]
	v_lshl_add_u64 v[84:85], v[84:85], 0, v[114:115]
	v_cvt_pk_bf16_f32 v82, v88, v89
	v_cvt_pk_bf16_f32 v83, v90, v91
	global_store_dwordx4 v[84:85], v[80:83], off
	v_pk_mul_f32 v[72:73], v[72:73], v[64:65]
	v_pk_mul_f32 v[76:77], v[76:77], v[68:69]
	v_mul_f32_e32 v80, 0xbfb8aa3b, v86
	v_pk_mul_f32 v[64:65], v[64:65], v[80:81] op_sel_hi:[1,0]
	v_pk_mul_f32 v[68:69], v[68:69], v[80:81] op_sel_hi:[1,0]
	v_pk_mul_f32 v[74:75], v[74:75], v[66:67]
	v_exp_f32_e32 v64, v64
	v_exp_f32_e32 v65, v65
	v_pk_mul_f32 v[66:67], v[66:67], v[80:81] op_sel_hi:[1,0]
	v_exp_f32_e32 v68, v68
	v_exp_f32_e32 v69, v69
	v_exp_f32_e32 v66, v66
	v_exp_f32_e32 v67, v67
	v_pk_fma_f32 v[64:65], v[64:65], v[238:239], v[238:239] op_sel_hi:[1,0,0]
	v_pk_fma_f32 v[68:69], v[68:69], v[238:239], v[238:239] op_sel_hi:[1,0,0]
	v_rcp_f32_e32 v64, v64
	v_rcp_f32_e32 v65, v65
	v_pk_fma_f32 v[66:67], v[66:67], v[238:239], v[238:239] op_sel_hi:[1,0,0]
	v_rcp_f32_e32 v68, v68
	v_rcp_f32_e32 v69, v69
	v_rcp_f32_e32 v66, v66
	v_rcp_f32_e32 v67, v67
	v_pk_mul_f32 v[72:73], v[72:73], v[64:65]
	v_pk_mul_f32 v[68:69], v[76:77], v[68:69]
	v_pk_mul_f32 v[74:75], v[74:75], v[66:67]
	v_pk_mul_f32 v[78:79], v[78:79], v[70:71]
	v_pk_mul_f32 v[70:71], v[70:71], v[80:81] op_sel_hi:[1,0]
	v_cvt_pk_bf16_f32 v64, v68, v69
	v_exp_f32_e32 v70, v70
	v_exp_f32_e32 v71, v71
	s_nop 0
	v_pk_fma_f32 v[70:71], v[70:71], v[238:239], v[238:239] op_sel_hi:[1,0,0]
	v_rcp_f32_e32 v70, v70
	v_rcp_f32_e32 v71, v71
	s_nop 0
	v_pk_mul_f32 v[70:71], v[78:79], v[70:71]
	v_cvt_f32_u32_e32 v172, v172
	v_cvt_f32_u32_e32 v173, v173
	v_fmamk_f32 v172, v173, 0x4f800000, v172
	v_fmamk_f32 v68, v172, 0x26800000, v193
	v_mov_b32_e32 v240, v68
	v_cvt_pk_bf16_f32 v65, v70, v71
	v_rsq_f32_e32 v70, v68
	v_mad_i64_i32 v[68:69], s[58:59], v170, s57, v[112:113]
	v_lshl_add_u64 v[68:69], v[68:69], 0, v[114:115]
	v_cvt_pk_bf16_f32 v66, v72, v73
	v_cvt_pk_bf16_f32 v67, v74, v75
	global_store_dwordx4 v[68:69], v[64:67], off
	v_pk_mul_f32 v[56:57], v[56:57], v[48:49]
	v_pk_mul_f32 v[60:61], v[60:61], v[52:53]
	v_mul_f32_e32 v64, 0xbfb8aa3b, v70
	v_pk_mul_f32 v[48:49], v[48:49], v[64:65] op_sel_hi:[1,0]
	v_pk_mul_f32 v[52:53], v[52:53], v[64:65] op_sel_hi:[1,0]
	v_pk_mul_f32 v[58:59], v[58:59], v[50:51]
	v_exp_f32_e32 v48, v48
	v_exp_f32_e32 v49, v49
	v_pk_mul_f32 v[50:51], v[50:51], v[64:65] op_sel_hi:[1,0]
	v_exp_f32_e32 v52, v52
	v_exp_f32_e32 v53, v53
	v_exp_f32_e32 v50, v50
	v_exp_f32_e32 v51, v51
	v_pk_fma_f32 v[48:49], v[48:49], v[240:241], v[240:241] op_sel_hi:[1,0,0]
	v_pk_fma_f32 v[52:53], v[52:53], v[240:241], v[240:241] op_sel_hi:[1,0,0]
	v_rcp_f32_e32 v48, v48
	v_rcp_f32_e32 v49, v49
	v_pk_fma_f32 v[50:51], v[50:51], v[240:241], v[240:241] op_sel_hi:[1,0,0]
	v_rcp_f32_e32 v52, v52
	v_rcp_f32_e32 v53, v53
	v_rcp_f32_e32 v50, v50
	v_rcp_f32_e32 v51, v51
	v_pk_mul_f32 v[56:57], v[56:57], v[48:49]
	v_pk_mul_f32 v[52:53], v[60:61], v[52:53]
	v_pk_mul_f32 v[58:59], v[58:59], v[50:51]
	v_pk_mul_f32 v[62:63], v[62:63], v[54:55]
	v_pk_mul_f32 v[54:55], v[54:55], v[64:65] op_sel_hi:[1,0]
	v_cvt_pk_bf16_f32 v48, v52, v53
	v_exp_f32_e32 v54, v54
	v_exp_f32_e32 v55, v55
	s_nop 0
	v_pk_fma_f32 v[54:55], v[54:55], v[240:241], v[240:241] op_sel_hi:[1,0,0]
	v_rcp_f32_e32 v54, v54
	v_rcp_f32_e32 v55, v55
	s_nop 0
	v_pk_mul_f32 v[54:55], v[62:63], v[54:55]
	v_cvt_f32_u32_e32 v168, v168
	v_cvt_f32_u32_e32 v169, v169
	v_fmamk_f32 v168, v169, 0x4f800000, v168
	v_fmamk_f32 v52, v168, 0x26800000, v193
	v_mov_b32_e32 v242, v52
	v_cvt_pk_bf16_f32 v49, v54, v55
	v_rsq_f32_e32 v54, v52
	v_add_u32_e32 v141, 0x80, v182
	v_mad_i64_i32 v[52:53], s[58:59], v141, s57, v[112:113]
	v_lshl_add_u64 v[52:53], v[52:53], 0, v[114:115]
	v_cvt_pk_bf16_f32 v50, v56, v57
	v_cvt_pk_bf16_f32 v51, v58, v59
	global_store_dwordx4 v[52:53], v[48:51], off
	v_pk_mul_f32 v[40:41], v[40:41], v[32:33]
	v_pk_mul_f32 v[44:45], v[44:45], v[36:37]
	v_mul_f32_e32 v48, 0xbfb8aa3b, v54
	v_pk_mul_f32 v[32:33], v[32:33], v[48:49] op_sel_hi:[1,0]
	v_pk_mul_f32 v[36:37], v[36:37], v[48:49] op_sel_hi:[1,0]
; __device__ __forceinline__ unsigned cvt_pk_bf16(float lo, float hi) { unsigned r; asm volatile("v_cvt_pk_bf16_f32 %0, %1, %2" : "=v"(r) : "v"(lo), "v"(hi)); return r; }
; __device__ __forceinline__ float ss_val(u64 v) { return (float)v * (1.0f / 1099511627776.0f); }
;     __device__ __forceinline__ void operator()(const f32x4 (&acc)[2][2][4][2], const Unit& u, const Unit& nxt, bool has_next, int wr, int wc, int fr, int fq) const {
;     ...
;         for (int g = 0; g < 8; ++g) {
;             const int ai = g >> 2, m = g & 3;
;             const float rs = __builtin_amdgcn_rsqf(ss_val(cur[g]) * inv_k + eps), rsn = rs * -1.44269504089f, rs2 = rs * rs;
;             float h[8];
; #pragma unroll
;             for (int n = 0; n < 2; ++n)
; #pragma unroll
;                 for (int jp = 0; jp < 2; ++jp) {
;                     const f32x2v av = {acc[ai][0][m][n][2 * jp], acc[ai][0][m][n][2 * jp + 1]}, gv = {acc[ai][1][m][n][2 * jp], acc[ai][1][m][n][2 * jp + 1]};
;                     const f32x2v t = (av * gv) * rs2, y = gv * rsn;
;                     f32x2v ex; ex.x = __builtin_amdgcn_exp2f(y.x); ex.y = __builtin_amdgcn_exp2f(y.y);
;                     const f32x2v d = ex + 1.0f;
;                     f32x2v r; r.x = __builtin_amdgcn_rcpf(d.x); r.y = __builtin_amdgcn_rcpf(d.y);
;                     const f32x2v o = t * r;
;                     h[4 * n + 2 * jp] = o.x; h[4 * n + 2 * jp + 1] = o.y;
;                 }
;             u32x4 w; w.x = cvt_pk_bf16(h[0], h[1]); w.y = cvt_pk_bf16(h[2], h[3]); w.z = cvt_pk_bf16(h[4], h[5]); w.w = cvt_pk_bf16(h[6], h[7]);
;             *(u32x4*)(O + (size_t)(row0 + ai * HALF + m * 16) * ldc + col0) = w;
;         }
;         if (has_next) { u64 x = 0;
; #pragma unroll
;             for (int g = 0; g < 8; ++g) x |= warm[g];
;             asm volatile("" :: "v"((unsigned)x), "v"((unsigned)(x >> 32))); }
	v_pk_mul_f32 v[42:43], v[42:43], v[34:35]
	v_exp_f32_e32 v32, v32
	v_exp_f32_e32 v33, v33
	v_pk_mul_f32 v[34:35], v[34:35], v[48:49] op_sel_hi:[1,0]
	v_exp_f32_e32 v36, v36
	v_exp_f32_e32 v37, v37
	v_exp_f32_e32 v34, v34
	v_exp_f32_e32 v35, v35
	v_pk_fma_f32 v[32:33], v[32:33], v[242:243], v[242:243] op_sel_hi:[1,0,0]
	v_pk_fma_f32 v[36:37], v[36:37], v[242:243], v[242:243] op_sel_hi:[1,0,0]
	v_rcp_f32_e32 v32, v32
	v_rcp_f32_e32 v33, v33
	v_pk_fma_f32 v[34:35], v[34:35], v[242:243], v[242:243] op_sel_hi:[1,0,0]
	v_rcp_f32_e32 v36, v36
	v_rcp_f32_e32 v37, v37
	v_rcp_f32_e32 v34, v34
	v_rcp_f32_e32 v35, v35
	v_pk_mul_f32 v[40:41], v[40:41], v[32:33]
	v_pk_mul_f32 v[36:37], v[44:45], v[36:37]
	v_pk_mul_f32 v[42:43], v[42:43], v[34:35]
	v_pk_mul_f32 v[46:47], v[46:47], v[38:39]
	v_pk_mul_f32 v[38:39], v[38:39], v[48:49] op_sel_hi:[1,0]
	v_cvt_pk_bf16_f32 v32, v36, v37
	v_exp_f32_e32 v38, v38
	v_exp_f32_e32 v39, v39
	s_nop 0
	v_pk_fma_f32 v[38:39], v[38:39], v[242:243], v[242:243] op_sel_hi:[1,0,0]
	v_rcp_f32_e32 v38, v38
	v_rcp_f32_e32 v39, v39
	s_nop 0
	v_pk_mul_f32 v[38:39], v[46:47], v[38:39]
	v_cvt_f32_u32_e32 v166, v166
	v_cvt_f32_u32_e32 v167, v167
	v_fmamk_f32 v166, v167, 0x4f800000, v166
	v_fmamk_f32 v36, v166, 0x26800000, v193
	v_mov_b32_e32 v244, v36
	v_cvt_pk_bf16_f32 v33, v38, v39
	v_rsq_f32_e32 v38, v36
	v_mad_i64_i32 v[36:37], s[58:59], v164, s57, v[112:113]
	v_lshl_add_u64 v[36:37], v[36:37], 0, v[114:115]
	v_cvt_pk_bf16_f32 v34, v40, v41
	v_cvt_pk_bf16_f32 v35, v42, v43
	global_store_dwordx4 v[36:37], v[32:35], off
	v_pk_mul_f32 v[24:25], v[24:25], v[16:17]
	v_pk_mul_f32 v[28:29], v[28:29], v[20:21]
	v_mul_f32_e32 v32, 0xbfb8aa3b, v38
	v_pk_mul_f32 v[16:17], v[16:17], v[32:33] op_sel_hi:[1,0]
	v_pk_mul_f32 v[20:21], v[20:21], v[32:33] op_sel_hi:[1,0]
	v_pk_mul_f32 v[26:27], v[26:27], v[18:19]
	v_exp_f32_e32 v16, v16
	v_exp_f32_e32 v17, v17
	v_pk_mul_f32 v[18:19], v[18:19], v[32:33] op_sel_hi:[1,0]
	v_exp_f32_e32 v20, v20
	v_exp_f32_e32 v21, v21
	v_exp_f32_e32 v18, v18
	v_exp_f32_e32 v19, v19
	v_pk_fma_f32 v[16:17], v[16:17], v[244:245], v[244:245] op_sel_hi:[1,0,0]
	v_pk_fma_f32 v[20:21], v[20:21], v[244:245], v[244:245] op_sel_hi:[1,0,0]
	v_rcp_f32_e32 v16, v16
	v_rcp_f32_e32 v17, v17
	v_pk_fma_f32 v[18:19], v[18:19], v[244:245], v[244:245] op_sel_hi:[1,0,0]
	v_rcp_f32_e32 v20, v20
	v_rcp_f32_e32 v21, v21
	v_rcp_f32_e32 v18, v18
	v_rcp_f32_e32 v19, v19
	v_pk_mul_f32 v[24:25], v[24:25], v[16:17]
	v_pk_mul_f32 v[20:21], v[28:29], v[20:21]
	v_pk_mul_f32 v[26:27], v[26:27], v[18:19]
	v_pk_mul_f32 v[30:31], v[30:31], v[22:23]
	v_pk_mul_f32 v[22:23], v[22:23], v[32:33] op_sel_hi:[1,0]
	v_cvt_pk_bf16_f32 v16, v20, v21
	v_exp_f32_e32 v22, v22
	v_exp_f32_e32 v23, v23
	s_nop 0
	v_pk_fma_f32 v[22:23], v[22:23], v[244:245], v[244:245] op_sel_hi:[1,0,0]
	v_rcp_f32_e32 v22, v22
	v_rcp_f32_e32 v23, v23
	s_nop 0
	v_pk_mul_f32 v[22:23], v[30:31], v[22:23]
	v_cvt_f32_u32_e32 v162, v162
	v_cvt_f32_u32_e32 v163, v163
	v_fmamk_f32 v162, v163, 0x4f800000, v162
	v_fmamk_f32 v20, v162, 0x26800000, v193
	v_mov_b32_e32 v246, v20
	v_cvt_pk_bf16_f32 v17, v22, v23
	v_rsq_f32_e32 v22, v20
	v_mad_i64_i32 v[20:21], s[58:59], v160, s57, v[112:113]
	v_lshl_add_u64 v[20:21], v[20:21], 0, v[114:115]
	v_cvt_pk_bf16_f32 v18, v24, v25
	v_cvt_pk_bf16_f32 v19, v26, v27
	global_store_dwordx4 v[20:21], v[16:19], off
	v_pk_mul_f32 v[12:13], v[12:13], v[4:5]
	v_pk_mul_f32 v[8:9], v[8:9], v[0:1]
	v_mul_f32_e32 v16, 0xbfb8aa3b, v22
	v_pk_mul_f32 v[4:5], v[4:5], v[16:17] op_sel_hi:[1,0]
	v_pk_mul_f32 v[0:1], v[0:1], v[16:17] op_sel_hi:[1,0]
	v_exp_f32_e32 v4, v4
	v_exp_f32_e32 v5, v5
	v_pk_mul_f32 v[10:11], v[10:11], v[2:3]
	v_exp_f32_e32 v0, v0
	v_exp_f32_e32 v1, v1
	v_pk_mul_f32 v[2:3], v[2:3], v[16:17] op_sel_hi:[1,0]
	v_pk_mul_f32 v[14:15], v[14:15], v[6:7]
	v_exp_f32_e32 v2, v2
	v_exp_f32_e32 v3, v3
	v_pk_mul_f32 v[6:7], v[6:7], v[16:17] op_sel_hi:[1,0]
	v_pk_fma_f32 v[4:5], v[4:5], v[246:247], v[246:247] op_sel_hi:[1,0,0]
	v_exp_f32_e32 v6, v6
	v_exp_f32_e32 v7, v7
	v_pk_fma_f32 v[0:1], v[0:1], v[246:247], v[246:247] op_sel_hi:[1,0,0]
	v_rcp_f32_e32 v4, v4
	v_rcp_f32_e32 v5, v5
	v_rcp_f32_e32 v0, v0
	v_rcp_f32_e32 v1, v1
	v_pk_fma_f32 v[2:3], v[2:3], v[246:247], v[246:247] op_sel_hi:[1,0,0]
	v_rcp_f32_e32 v2, v2
	v_rcp_f32_e32 v3, v3
	v_pk_fma_f32 v[6:7], v[6:7], v[246:247], v[246:247] op_sel_hi:[1,0,0]
	v_rcp_f32_e32 v6, v6
	v_rcp_f32_e32 v7, v7
	v_pk_mul_f32 v[4:5], v[12:13], v[4:5]
	v_pk_mul_f32 v[8:9], v[8:9], v[0:1]
	v_pk_mul_f32 v[10:11], v[10:11], v[2:3]
	v_cvt_pk_bf16_f32 v0, v4, v5
	v_mad_i64_i32 v[4:5], s[58:59], v140, s57, v[112:113]
	v_lshl_add_u64 v[4:5], v[4:5], 0, v[114:115]
	s_and_b64 vcc, exec, s[4:5]
	s_mov_b64 s[4:5], -1
	v_pk_mul_f32 v[6:7], v[14:15], v[6:7]
	s_nop 0
	v_cvt_pk_bf16_f32 v1, v6, v7
	v_cvt_pk_bf16_f32 v2, v8, v9
	v_cvt_pk_bf16_f32 v3, v10, v11
	global_store_dwordx4 v[4:5], v[0:3], off
	s_cbranch_vccnz .LBB0_656
	s_nop 0
	v_or_b32_e32 v0, v159, v157
	v_or_b32_e32 v1, v158, v156
	v_or3_b32 v0, v0, v153, v155
	v_or3_b32 v1, v1, v152, v154
	v_or3_b32 v0, v0, v149, v151
	v_or3_b32 v1, v1, v148, v150
	s_andn2_b64 vcc, exec, s[6:7]
	v_or3_b32 v0, v0, v143, v147
	v_or3_b32 v1, v1, v142, v146
	s_cbranch_vccnz .LBB0_655
	s_barrier
	s_branch .LBB0_655

;     __device__ __forceinline__ void operator()(const f32x4 (&acc)[2][2][4][2], const Unit& u, const Unit& nxt, bool has_next, int wr, int wc, int fr, int fq) const {
;         const int row0 = u.pm * BM + wr * 64 + fr, col0 = u.pn * HALF + wc * 32 + 8 * fq;
;         u64 cur[8], warm[8];
; #pragma unroll
;         for (int g = 0; g < 8; ++g) cur[g] = rowss[row0 + (g >> 2) * HALF + (g & 3) * 16];
;         if (has_next) {
; #pragma unroll
;             for (int g = 0; g < 8; ++g) warm[g] = rowss[nxt.pm * BM + wr * 64 + fr + (g >> 2) * HALF + (g & 3) * 16];
.LBB0_813:
	s_waitcnt vmcnt(0)
	s_cbranch_vccz .Lepf_skip_2
	v_mov_b32_e32 v232, s95
	v_lshlrev_b32_e32 v232, 3, v232
	v_add_u32_e32 v232, s97, v232
	v_lshl_add_u32 v232, v232, 6, v200
	v_lshrrev_b32_e32 v231, 1, v232
	v_min_u32_e32 v231, 0x3ff, v231
	v_mul_u32_u24_e32 v231, 0x1600, v231
	v_and_b32_e32 v232, 1, v232
	v_lshlrev_b32_e32 v232, 7, v232
	v_add_u32_e32 v232, v231, v232
	v_add_u32_e32 v232, 0x3b80000, v232
	global_load_dword v231, v232, s[34:35]
	v_readlane_b32 s101, v230, 6
	s_nop 3
	s_mul_i32 s101, s101, 704
	s_add_u32 s101, s101, 0xa000000
	v_mov_b32_e32 v233, s97
	v_lshl_add_u32 v233, v233, 6, v200
	v_mov_b32_e32 v234, s95
	v_lshrrev_b32_e32 v235, 4, v234
	v_and_b32_e32 v234, 3, v234
	v_lshl_or_b32 v234, v235, 2, v234
	v_lshlrev_b32_e32 v234, 8, v234
	v_lshrrev_b32_e32 v235, 1, v233
	v_add_u32_e32 v234, v234, v235
	v_mul_u32_u24_e32 v234, 0x1600, v234
	v_and_b32_e32 v233, 1, v233
	v_lshlrev_b32_e32 v233, 7, v233
	v_add3_u32 v233, v234, v233, s101
	global_load_dword v235, v233, s[34:35]

; __device__ __forceinline__ unsigned cvt_pk_bf16(float lo, float hi) { unsigned r; asm volatile("v_cvt_pk_bf16_f32 %0, %1, %2" : "=v"(r) : "v"(lo), "v"(hi)); return r; }
; __device__ __forceinline__ float ss_val(u64 v) { return (float)v * (1.0f / 1099511627776.0f); }
;     __device__ __forceinline__ void operator()(const f32x4 (&acc)[2][2][4][2], const Unit& u, const Unit& nxt, bool has_next, int wr, int wc, int fr, int fq) const {
;         const int row0 = u.pm * BM + wr * 64 + fr, col0 = u.pn * HALF + wc * 32 + 8 * fq;
;         u64 cur[8], warm[8];
; #pragma unroll
;         for (int g = 0; g < 8; ++g) cur[g] = rowss[row0 + (g >> 2) * HALF + (g & 3) * 16];
;         if (has_next) {
; #pragma unroll
;             for (int g = 0; g < 8; ++g) warm[g] = rowss[nxt.pm * BM + wr * 64 + fr + (g >> 2) * HALF + (g & 3) * 16];
;         }
; #pragma unroll
;         for (int g = 0; g < 8; ++g) {
;             const int ai = g >> 2, m = g & 3;
;             const float rs = __builtin_amdgcn_rsqf(ss_val(cur[g]) * inv_k + eps), rsn = rs * -1.44269504089f, rs2 = rs * rs;
;             float h[8];
; #pragma unroll
;             for (int n = 0; n < 2; ++n)
; #pragma unroll
;                 for (int jp = 0; jp < 2; ++jp) {
;                     const f32x2v av = {acc[ai][0][m][n][2 * jp], acc[ai][0][m][n][2 * jp + 1]}, gv = {acc[ai][1][m][n][2 * jp], acc[ai][1][m][n][2 * jp + 1]};
;                     const f32x2v t = (av * gv) * rs2, y = gv * rsn;
;                     f32x2v ex; ex.x = __builtin_amdgcn_exp2f(y.x); ex.y = __builtin_amdgcn_exp2f(y.y);
;                     const f32x2v d = ex + 1.0f;
;                     f32x2v r; r.x = __builtin_amdgcn_rcpf(d.x); r.y = __builtin_amdgcn_rcpf(d.y);
;                     const f32x2v o = t * r;
;                     h[4 * n + 2 * jp] = o.x; h[4 * n + 2 * jp + 1] = o.y;
;                 }
;             u32x4 w; w.x = cvt_pk_bf16(h[0], h[1]); w.y = cvt_pk_bf16(h[2], h[3]); w.z = cvt_pk_bf16(h[4], h[5]); w.w = cvt_pk_bf16(h[6], h[7]);
;             *(u32x4*)(O + (size_t)(row0 + ai * HALF + m * 16) * ldc + col0) = w;
;         }
.LBB0_1298:
	s_waitcnt vmcnt(0)
	s_cbranch_vccz .Lepf_skip_3
	v_mov_b32_e32 v232, s95
	v_lshlrev_b32_e32 v232, 3, v232
	v_add_u32_e32 v232, s97, v232
	v_lshl_add_u32 v232, v232, 6, v200
	v_lshrrev_b32_e32 v231, 1, v232
	v_min_u32_e32 v231, 0x3ff, v231
	v_mul_u32_u24_e32 v231, 0x1600, v231
	v_and_b32_e32 v232, 1, v232
	v_lshlrev_b32_e32 v232, 7, v232
	v_add_u32_e32 v232, v231, v232
	v_add_u32_e32 v232, 0x5380000, v232
	global_load_dword v231, v232, s[34:35]
	v_readlane_b32 s101, v230, 6
	s_nop 3
	s_mul_i32 s101, s101, 704
	s_add_u32 s101, s101, 0xa000000
	v_mov_b32_e32 v233, s97
	v_lshl_add_u32 v233, v233, 6, v200
	v_mov_b32_e32 v234, s95
	v_lshrrev_b32_e32 v235, 4, v234
	v_and_b32_e32 v234, 3, v234
	v_lshl_or_b32 v234, v235, 2, v234
	v_lshlrev_b32_e32 v234, 8, v234
	v_lshrrev_b32_e32 v235, 1, v233
	v_add_u32_e32 v234, v234, v235
	v_mul_u32_u24_e32 v234, 0x1600, v234
	v_and_b32_e32 v233, 1, v233
	v_lshlrev_b32_e32 v233, 7, v233
	v_add3_u32 v233, v234, v233, s101
	global_load_dword v235, v233, s[34:35]
.Lepf_skip_3:
	v_pk_mul_f32 v[124:125], v[124:125], v[116:117]
	v_pk_mul_f32 v[120:121], v[120:121], v[112:113]
	v_cvt_f32_u32_e32 v184, v184
	v_cvt_f32_u32_e32 v185, v185
	v_fmamk_f32 v184, v185, 0x4f800000, v184
	v_fmamk_f32 v159, v184, 0x26800000, v192
	v_mov_b32_e32 v232, v159
	v_rsq_f32_e32 v159, v159
	v_pk_mul_f32 v[126:127], v[126:127], v[118:119]
	v_pk_mul_f32 v[122:123], v[122:123], v[114:115]
	v_lshl_or_b32 v184, s62, 7, v188
	v_mul_f32_e32 v194, 0xbfb8aa3b, v159
	v_pk_mul_f32 v[116:117], v[116:117], v[194:195] op_sel_hi:[1,0]
	v_pk_mul_f32 v[112:113], v[112:113], v[194:195] op_sel_hi:[1,0]
	v_exp_f32_e32 v116, v116
	v_exp_f32_e32 v117, v117
	v_pk_mul_f32 v[118:119], v[118:119], v[194:195] op_sel_hi:[1,0]
	v_exp_f32_e32 v112, v112
	v_exp_f32_e32 v113, v113
	v_pk_mul_f32 v[114:115], v[114:115], v[194:195] op_sel_hi:[1,0]
	v_exp_f32_e32 v118, v118
	v_exp_f32_e32 v119, v119
	v_exp_f32_e32 v114, v114
	v_exp_f32_e32 v115, v115
	v_pk_fma_f32 v[116:117], v[116:117], v[232:233], v[232:233] op_sel_hi:[1,0,0]
	v_pk_fma_f32 v[112:113], v[112:113], v[232:233], v[232:233] op_sel_hi:[1,0,0]
	v_rcp_f32_e32 v116, v116
	v_rcp_f32_e32 v117, v117
	v_pk_fma_f32 v[118:119], v[118:119], v[232:233], v[232:233] op_sel_hi:[1,0,0]
	v_rcp_f32_e32 v112, v112
	v_rcp_f32_e32 v113, v113
	v_pk_fma_f32 v[114:115], v[114:115], v[232:233], v[232:233] op_sel_hi:[1,0,0]
	v_rcp_f32_e32 v118, v118
	v_rcp_f32_e32 v119, v119
	v_rcp_f32_e32 v114, v114
	v_rcp_f32_e32 v115, v115
	v_pk_mul_f32 v[116:117], v[124:125], v[116:117]
	v_pk_mul_f32 v[112:113], v[120:121], v[112:113]
	v_pk_mul_f32 v[118:119], v[126:127], v[118:119]
	v_pk_mul_f32 v[114:115], v[122:123], v[114:115]
	v_cvt_pk_bf16_f32 v116, v116, v117
	v_cvt_pk_bf16_f32 v117, v118, v119
	v_cvt_pk_bf16_f32 v118, v112, v113
	v_ashrrev_i32_e32 v185, 31, v184
	v_cvt_pk_bf16_f32 v119, v114, v115
	v_mov_b64_e32 v[112:113], s[24:25]
	v_mad_i64_i32 v[120:121], s[46:47], v180, s61, v[112:113]
	v_cvt_f32_u32_e32 v182, v182
	v_cvt_f32_u32_e32 v183, v183
	v_fmamk_f32 v182, v183, 0x4f800000, v182
	v_fmamk_f32 v114, v182, 0x26800000, v192
	v_mov_b32_e32 v234, v114
	v_rsq_f32_e32 v122, v114
	v_lshlrev_b64 v[114:115], 1, v[184:185]
	v_lshl_add_u64 v[120:121], v[120:121], 0, v[114:115]
	global_store_dwordx4 v[120:121], v[116:119], off
	v_pk_mul_f32 v[104:105], v[104:105], v[96:97]
	v_pk_mul_f32 v[108:109], v[108:109], v[100:101]
	v_mul_f32_e32 v116, 0xbfb8aa3b, v122
	v_pk_mul_f32 v[96:97], v[96:97], v[116:117] op_sel_hi:[1,0]
	v_pk_mul_f32 v[100:101], v[100:101], v[116:117] op_sel_hi:[1,0]
	v_pk_mul_f32 v[106:107], v[106:107], v[98:99]
	v_exp_f32_e32 v96, v96
	v_exp_f32_e32 v97, v97
	v_pk_mul_f32 v[98:99], v[98:99], v[116:117] op_sel_hi:[1,0]
	v_exp_f32_e32 v100, v100
	v_exp_f32_e32 v101, v101
	v_exp_f32_e32 v98, v98
	v_exp_f32_e32 v99, v99
	v_pk_fma_f32 v[96:97], v[96:97], v[234:235], v[234:235] op_sel_hi:[1,0,0]
	v_pk_fma_f32 v[100:101], v[100:101], v[234:235], v[234:235] op_sel_hi:[1,0,0]
	v_rcp_f32_e32 v96, v96
	v_rcp_f32_e32 v97, v97
	v_pk_fma_f32 v[98:99], v[98:99], v[234:235], v[234:235] op_sel_hi:[1,0,0]
	v_rcp_f32_e32 v100, v100
	v_rcp_f32_e32 v101, v101
	v_rcp_f32_e32 v98, v98
	v_rcp_f32_e32 v99, v99
	v_pk_mul_f32 v[104:105], v[104:105], v[96:97]
	v_pk_mul_f32 v[100:101], v[108:109], v[100:101]
	v_pk_mul_f32 v[106:107], v[106:107], v[98:99]
	v_pk_mul_f32 v[110:111], v[110:111], v[102:103]
	v_pk_mul_f32 v[102:103], v[102:103], v[116:117] op_sel_hi:[1,0]
	v_cvt_pk_bf16_f32 v96, v100, v101
	v_exp_f32_e32 v102, v102
	v_exp_f32_e32 v103, v103
	s_nop 0
	v_pk_fma_f32 v[102:103], v[102:103], v[234:235], v[234:235] op_sel_hi:[1,0,0]
	v_rcp_f32_e32 v102, v102
	v_rcp_f32_e32 v103, v103
	s_nop 0
	v_pk_mul_f32 v[102:103], v[110:111], v[102:103]
	v_cvt_f32_u32_e32 v178, v178
	v_cvt_f32_u32_e32 v179, v179
	v_fmamk_f32 v178, v179, 0x4f800000, v178
	v_fmamk_f32 v100, v178, 0x26800000, v192
	v_mov_b32_e32 v236, v100
	v_cvt_pk_bf16_f32 v97, v102, v103
	v_rsq_f32_e32 v102, v100
	v_mad_i64_i32 v[100:101], s[46:47], v176, s61, v[112:113]
	v_lshl_add_u64 v[100:101], v[100:101], 0, v[114:115]
	v_cvt_pk_bf16_f32 v98, v104, v105
	v_cvt_pk_bf16_f32 v99, v106, v107
	global_store_dwordx4 v[100:101], v[96:99], off
	v_pk_mul_f32 v[88:89], v[88:89], v[80:81]
	v_pk_mul_f32 v[92:93], v[92:93], v[84:85]
	v_mul_f32_e32 v96, 0xbfb8aa3b, v102
	v_pk_mul_f32 v[80:81], v[80:81], v[96:97] op_sel_hi:[1,0]
	v_pk_mul_f32 v[84:85], v[84:85], v[96:97] op_sel_hi:[1,0]
	v_pk_mul_f32 v[90:91], v[90:91], v[82:83]
	v_exp_f32_e32 v80, v80
	v_exp_f32_e32 v81, v81
	v_pk_mul_f32 v[82:83], v[82:83], v[96:97] op_sel_hi:[1,0]
	v_exp_f32_e32 v84, v84
	v_exp_f32_e32 v85, v85
; __device__ __forceinline__ unsigned cvt_pk_bf16(float lo, float hi) { unsigned r; asm volatile("v_cvt_pk_bf16_f32 %0, %1, %2" : "=v"(r) : "v"(lo), "v"(hi)); return r; }
; __device__ __forceinline__ float ss_val(u64 v) { return (float)v * (1.0f / 1099511627776.0f); }
;     __device__ __forceinline__ void operator()(const f32x4 (&acc)[2][2][4][2], const Unit& u, const Unit& nxt, bool has_next, int wr, int wc, int fr, int fq) const {
;     ...
;         for (int g = 0; g < 8; ++g) {
;             const int ai = g >> 2, m = g & 3;
;             const float rs = __builtin_amdgcn_rsqf(ss_val(cur[g]) * inv_k + eps), rsn = rs * -1.44269504089f, rs2 = rs * rs;
;             float h[8];
; #pragma unroll
;             for (int n = 0; n < 2; ++n)
; #pragma unroll
;                 for (int jp = 0; jp < 2; ++jp) {
;                     const f32x2v av = {acc[ai][0][m][n][2 * jp], acc[ai][0][m][n][2 * jp + 1]}, gv = {acc[ai][1][m][n][2 * jp], acc[ai][1][m][n][2 * jp + 1]};
;                     const f32x2v t = (av * gv) * rs2, y = gv * rsn;
;                     f32x2v ex; ex.x = __builtin_amdgcn_exp2f(y.x); ex.y = __builtin_amdgcn_exp2f(y.y);
;                     const f32x2v d = ex + 1.0f;
;                     f32x2v r; r.x = __builtin_amdgcn_rcpf(d.x); r.y = __builtin_amdgcn_rcpf(d.y);
;                     const f32x2v o = t * r;
;                     h[4 * n + 2 * jp] = o.x; h[4 * n + 2 * jp + 1] = o.y;
;                 }
;             u32x4 w; w.x = cvt_pk_bf16(h[0], h[1]); w.y = cvt_pk_bf16(h[2], h[3]); w.z = cvt_pk_bf16(h[4], h[5]); w.w = cvt_pk_bf16(h[6], h[7]);
;             *(u32x4*)(O + (size_t)(row0 + ai * HALF + m * 16) * ldc + col0) = w;
;         }
	v_exp_f32_e32 v82, v82
	v_exp_f32_e32 v83, v83
	v_pk_fma_f32 v[80:81], v[80:81], v[236:237], v[236:237] op_sel_hi:[1,0,0]
	v_pk_fma_f32 v[84:85], v[84:85], v[236:237], v[236:237] op_sel_hi:[1,0,0]
	v_rcp_f32_e32 v80, v80
	v_rcp_f32_e32 v81, v81
	v_pk_fma_f32 v[82:83], v[82:83], v[236:237], v[236:237] op_sel_hi:[1,0,0]
	v_rcp_f32_e32 v84, v84
	v_rcp_f32_e32 v85, v85
	v_rcp_f32_e32 v82, v82
	v_rcp_f32_e32 v83, v83
	v_pk_mul_f32 v[88:89], v[88:89], v[80:81]
	v_pk_mul_f32 v[84:85], v[92:93], v[84:85]
	v_pk_mul_f32 v[90:91], v[90:91], v[82:83]
	v_pk_mul_f32 v[94:95], v[94:95], v[86:87]
	v_pk_mul_f32 v[86:87], v[86:87], v[96:97] op_sel_hi:[1,0]
	v_cvt_pk_bf16_f32 v80, v84, v85
	v_exp_f32_e32 v86, v86
	v_exp_f32_e32 v87, v87
	s_nop 0
	v_pk_fma_f32 v[86:87], v[86:87], v[236:237], v[236:237] op_sel_hi:[1,0,0]
	v_rcp_f32_e32 v86, v86
	v_rcp_f32_e32 v87, v87
	s_nop 0
	v_pk_mul_f32 v[86:87], v[94:95], v[86:87]
	v_cvt_f32_u32_e32 v174, v174
	v_cvt_f32_u32_e32 v175, v175
	v_fmamk_f32 v174, v175, 0x4f800000, v174
	v_fmamk_f32 v84, v174, 0x26800000, v192
	v_mov_b32_e32 v238, v84
	v_cvt_pk_bf16_f32 v81, v86, v87
	v_rsq_f32_e32 v86, v84
	v_mad_i64_i32 v[84:85], s[46:47], v172, s61, v[112:113]
	v_lshl_add_u64 v[84:85], v[84:85], 0, v[114:115]
	v_cvt_pk_bf16_f32 v82, v88, v89
	v_cvt_pk_bf16_f32 v83, v90, v91
	global_store_dwordx4 v[84:85], v[80:83], off
	v_pk_mul_f32 v[72:73], v[72:73], v[64:65]
	v_pk_mul_f32 v[76:77], v[76:77], v[68:69]
	v_mul_f32_e32 v80, 0xbfb8aa3b, v86
	v_pk_mul_f32 v[64:65], v[64:65], v[80:81] op_sel_hi:[1,0]
	v_pk_mul_f32 v[68:69], v[68:69], v[80:81] op_sel_hi:[1,0]
	v_pk_mul_f32 v[74:75], v[74:75], v[66:67]
	v_exp_f32_e32 v64, v64
	v_exp_f32_e32 v65, v65
	v_pk_mul_f32 v[66:67], v[66:67], v[80:81] op_sel_hi:[1,0]
	v_exp_f32_e32 v68, v68
	v_exp_f32_e32 v69, v69
	v_exp_f32_e32 v66, v66
	v_exp_f32_e32 v67, v67
	v_pk_fma_f32 v[64:65], v[64:65], v[238:239], v[238:239] op_sel_hi:[1,0,0]
	v_pk_fma_f32 v[68:69], v[68:69], v[238:239], v[238:239] op_sel_hi:[1,0,0]
	v_rcp_f32_e32 v64, v64
	v_rcp_f32_e32 v65, v65
	v_pk_fma_f32 v[66:67], v[66:67], v[238:239], v[238:239] op_sel_hi:[1,0,0]
	v_rcp_f32_e32 v68, v68
	v_rcp_f32_e32 v69, v69
	v_rcp_f32_e32 v66, v66
	v_rcp_f32_e32 v67, v67
	v_pk_mul_f32 v[72:73], v[72:73], v[64:65]
	v_pk_mul_f32 v[68:69], v[76:77], v[68:69]
	v_pk_mul_f32 v[74:75], v[74:75], v[66:67]
	v_pk_mul_f32 v[78:79], v[78:79], v[70:71]
	v_pk_mul_f32 v[70:71], v[70:71], v[80:81] op_sel_hi:[1,0]
	v_cvt_pk_bf16_f32 v64, v68, v69
	v_exp_f32_e32 v70, v70
	v_exp_f32_e32 v71, v71
	s_nop 0
	v_pk_fma_f32 v[70:71], v[70:71], v[238:239], v[238:239] op_sel_hi:[1,0,0]
	v_rcp_f32_e32 v70, v70
	v_rcp_f32_e32 v71, v71
	s_nop 0
	v_pk_mul_f32 v[70:71], v[78:79], v[70:71]
	v_cvt_f32_u32_e32 v170, v170
	v_cvt_f32_u32_e32 v171, v171
	v_fmamk_f32 v170, v171, 0x4f800000, v170
	v_fmamk_f32 v68, v170, 0x26800000, v192
	v_mov_b32_e32 v240, v68
	v_cvt_pk_bf16_f32 v65, v70, v71
	v_rsq_f32_e32 v70, v68
	v_mad_i64_i32 v[68:69], s[46:47], v168, s61, v[112:113]
	v_lshl_add_u64 v[68:69], v[68:69], 0, v[114:115]
	v_cvt_pk_bf16_f32 v66, v72, v73
	v_cvt_pk_bf16_f32 v67, v74, v75
	global_store_dwordx4 v[68:69], v[64:67], off
	v_pk_mul_f32 v[56:57], v[56:57], v[48:49]
	v_pk_mul_f32 v[60:61], v[60:61], v[52:53]
	v_mul_f32_e32 v64, 0xbfb8aa3b, v70
	v_pk_mul_f32 v[48:49], v[48:49], v[64:65] op_sel_hi:[1,0]
	v_pk_mul_f32 v[52:53], v[52:53], v[64:65] op_sel_hi:[1,0]
	v_pk_mul_f32 v[58:59], v[58:59], v[50:51]
	v_exp_f32_e32 v48, v48
	v_exp_f32_e32 v49, v49
	v_pk_mul_f32 v[50:51], v[50:51], v[64:65] op_sel_hi:[1,0]
	v_exp_f32_e32 v52, v52
	v_exp_f32_e32 v53, v53
	v_exp_f32_e32 v50, v50
	v_exp_f32_e32 v51, v51
	v_pk_fma_f32 v[48:49], v[48:49], v[240:241], v[240:241] op_sel_hi:[1,0,0]
	v_pk_fma_f32 v[52:53], v[52:53], v[240:241], v[240:241] op_sel_hi:[1,0,0]
	v_rcp_f32_e32 v48, v48
	v_rcp_f32_e32 v49, v49
	v_pk_fma_f32 v[50:51], v[50:51], v[240:241], v[240:241] op_sel_hi:[1,0,0]
	v_rcp_f32_e32 v52, v52
	v_rcp_f32_e32 v53, v53
	v_rcp_f32_e32 v50, v50
	v_rcp_f32_e32 v51, v51
	v_pk_mul_f32 v[56:57], v[56:57], v[48:49]
	v_pk_mul_f32 v[52:53], v[60:61], v[52:53]
	v_pk_mul_f32 v[58:59], v[58:59], v[50:51]
	v_pk_mul_f32 v[62:63], v[62:63], v[54:55]
	v_pk_mul_f32 v[54:55], v[54:55], v[64:65] op_sel_hi:[1,0]
	v_cvt_pk_bf16_f32 v48, v52, v53
	v_exp_f32_e32 v54, v54
	v_exp_f32_e32 v55, v55
	s_nop 0
	v_pk_fma_f32 v[54:55], v[54:55], v[240:241], v[240:241] op_sel_hi:[1,0,0]
	v_rcp_f32_e32 v54, v54
	v_rcp_f32_e32 v55, v55
	s_nop 0
	v_pk_mul_f32 v[54:55], v[62:63], v[54:55]
	v_cvt_f32_u32_e32 v166, v166
	v_cvt_f32_u32_e32 v167, v167
	v_fmamk_f32 v166, v167, 0x4f800000, v166
	v_fmamk_f32 v52, v166, 0x26800000, v192
	v_mov_b32_e32 v242, v52
	v_cvt_pk_bf16_f32 v49, v54, v55
	v_rsq_f32_e32 v54, v52
	v_add_u32_e32 v141, 0x80, v180
	v_mad_i64_i32 v[52:53], s[46:47], v141, s61, v[112:113]
	v_lshl_add_u64 v[52:53], v[52:53], 0, v[114:115]
	v_cvt_pk_bf16_f32 v50, v56, v57
	v_cvt_pk_bf16_f32 v51, v58, v59
	global_store_dwordx4 v[52:53], v[48:51], off
	v_pk_mul_f32 v[40:41], v[40:41], v[32:33]
	v_pk_mul_f32 v[44:45], v[44:45], v[36:37]
	v_mul_f32_e32 v48, 0xbfb8aa3b, v54
	v_pk_mul_f32 v[32:33], v[32:33], v[48:49] op_sel_hi:[1,0]
	v_pk_mul_f32 v[36:37], v[36:37], v[48:49] op_sel_hi:[1,0]
; __device__ __forceinline__ unsigned cvt_pk_bf16(float lo, float hi) { unsigned r; asm volatile("v_cvt_pk_bf16_f32 %0, %1, %2" : "=v"(r) : "v"(lo), "v"(hi)); return r; }
; __device__ __forceinline__ float ss_val(u64 v) { return (float)v * (1.0f / 1099511627776.0f); }
;     __device__ __forceinline__ void operator()(const f32x4 (&acc)[2][2][4][2], const Unit& u, const Unit& nxt, bool has_next, int wr, int wc, int fr, int fq) const {
;     ...
;         for (int g = 0; g < 8; ++g) {
;             const int ai = g >> 2, m = g & 3;
;             const float rs = __builtin_amdgcn_rsqf(ss_val(cur[g]) * inv_k + eps), rsn = rs * -1.44269504089f, rs2 = rs * rs;
;             float h[8];
; #pragma unroll
;             for (int n = 0; n < 2; ++n)
; #pragma unroll
;                 for (int jp = 0; jp < 2; ++jp) {
;                     const f32x2v av = {acc[ai][0][m][n][2 * jp], acc[ai][0][m][n][2 * jp + 1]}, gv = {acc[ai][1][m][n][2 * jp], acc[ai][1][m][n][2 * jp + 1]};
;                     const f32x2v t = (av * gv) * rs2, y = gv * rsn;
;                     f32x2v ex; ex.x = __builtin_amdgcn_exp2f(y.x); ex.y = __builtin_amdgcn_exp2f(y.y);
;                     const f32x2v d = ex + 1.0f;
;                     f32x2v r; r.x = __builtin_amdgcn_rcpf(d.x); r.y = __builtin_amdgcn_rcpf(d.y);
;                     const f32x2v o = t * r;
;                     h[4 * n + 2 * jp] = o.x; h[4 * n + 2 * jp + 1] = o.y;
;                 }
;             u32x4 w; w.x = cvt_pk_bf16(h[0], h[1]); w.y = cvt_pk_bf16(h[2], h[3]); w.z = cvt_pk_bf16(h[4], h[5]); w.w = cvt_pk_bf16(h[6], h[7]);
;             *(u32x4*)(O + (size_t)(row0 + ai * HALF + m * 16) * ldc + col0) = w;
;         }
;         if (has_next) { u64 x = 0;
; #pragma unroll
;             for (int g = 0; g < 8; ++g) x |= warm[g];
;             asm volatile("" :: "v"((unsigned)x), "v"((unsigned)(x >> 32))); }
	v_pk_mul_f32 v[42:43], v[42:43], v[34:35]
	v_exp_f32_e32 v32, v32
	v_exp_f32_e32 v33, v33
	v_pk_mul_f32 v[34:35], v[34:35], v[48:49] op_sel_hi:[1,0]
	v_exp_f32_e32 v36, v36
	v_exp_f32_e32 v37, v37
	v_exp_f32_e32 v34, v34
	v_exp_f32_e32 v35, v35
	v_pk_fma_f32 v[32:33], v[32:33], v[242:243], v[242:243] op_sel_hi:[1,0,0]
	v_pk_fma_f32 v[36:37], v[36:37], v[242:243], v[242:243] op_sel_hi:[1,0,0]
	v_rcp_f32_e32 v32, v32
	v_rcp_f32_e32 v33, v33
	v_pk_fma_f32 v[34:35], v[34:35], v[242:243], v[242:243] op_sel_hi:[1,0,0]
	v_rcp_f32_e32 v36, v36
	v_rcp_f32_e32 v37, v37
	v_rcp_f32_e32 v34, v34
	v_rcp_f32_e32 v35, v35
	v_pk_mul_f32 v[40:41], v[40:41], v[32:33]
	v_pk_mul_f32 v[36:37], v[44:45], v[36:37]
	v_pk_mul_f32 v[42:43], v[42:43], v[34:35]
	v_pk_mul_f32 v[46:47], v[46:47], v[38:39]
	v_pk_mul_f32 v[38:39], v[38:39], v[48:49] op_sel_hi:[1,0]
	v_cvt_pk_bf16_f32 v32, v36, v37
	v_exp_f32_e32 v38, v38
	v_exp_f32_e32 v39, v39
	s_nop 0
	v_pk_fma_f32 v[38:39], v[38:39], v[242:243], v[242:243] op_sel_hi:[1,0,0]
	v_rcp_f32_e32 v38, v38
	v_rcp_f32_e32 v39, v39
	s_nop 0
	v_pk_mul_f32 v[38:39], v[46:47], v[38:39]
	v_cvt_f32_u32_e32 v164, v164
	v_cvt_f32_u32_e32 v165, v165
	v_fmamk_f32 v164, v165, 0x4f800000, v164
	v_fmamk_f32 v36, v164, 0x26800000, v192
	v_mov_b32_e32 v244, v36
	v_cvt_pk_bf16_f32 v33, v38, v39
	v_rsq_f32_e32 v38, v36
	v_mad_i64_i32 v[36:37], s[46:47], v162, s61, v[112:113]
	v_lshl_add_u64 v[36:37], v[36:37], 0, v[114:115]
	v_cvt_pk_bf16_f32 v34, v40, v41
	v_cvt_pk_bf16_f32 v35, v42, v43
	global_store_dwordx4 v[36:37], v[32:35], off
	v_pk_mul_f32 v[24:25], v[24:25], v[16:17]
	v_pk_mul_f32 v[28:29], v[28:29], v[20:21]
	v_mul_f32_e32 v32, 0xbfb8aa3b, v38
	v_pk_mul_f32 v[16:17], v[16:17], v[32:33] op_sel_hi:[1,0]
	v_pk_mul_f32 v[20:21], v[20:21], v[32:33] op_sel_hi:[1,0]
	v_pk_mul_f32 v[26:27], v[26:27], v[18:19]
	v_exp_f32_e32 v16, v16
	v_exp_f32_e32 v17, v17
	v_pk_mul_f32 v[18:19], v[18:19], v[32:33] op_sel_hi:[1,0]
	v_exp_f32_e32 v20, v20
	v_exp_f32_e32 v21, v21
	v_exp_f32_e32 v18, v18
	v_exp_f32_e32 v19, v19
	v_pk_fma_f32 v[16:17], v[16:17], v[244:245], v[244:245] op_sel_hi:[1,0,0]
	v_pk_fma_f32 v[20:21], v[20:21], v[244:245], v[244:245] op_sel_hi:[1,0,0]
	v_rcp_f32_e32 v16, v16
	v_rcp_f32_e32 v17, v17
	v_pk_fma_f32 v[18:19], v[18:19], v[244:245], v[244:245] op_sel_hi:[1,0,0]
	v_rcp_f32_e32 v20, v20
	v_rcp_f32_e32 v21, v21
	v_rcp_f32_e32 v18, v18
	v_rcp_f32_e32 v19, v19
	v_pk_mul_f32 v[24:25], v[24:25], v[16:17]
	v_pk_mul_f32 v[20:21], v[28:29], v[20:21]
	v_pk_mul_f32 v[26:27], v[26:27], v[18:19]
	v_pk_mul_f32 v[30:31], v[30:31], v[22:23]
	v_pk_mul_f32 v[22:23], v[22:23], v[32:33] op_sel_hi:[1,0]
	v_cvt_pk_bf16_f32 v16, v20, v21
	v_exp_f32_e32 v22, v22
	v_exp_f32_e32 v23, v23
	s_nop 0
	v_pk_fma_f32 v[22:23], v[22:23], v[244:245], v[244:245] op_sel_hi:[1,0,0]
	v_rcp_f32_e32 v22, v22
	v_rcp_f32_e32 v23, v23
	s_nop 0
	v_pk_mul_f32 v[22:23], v[30:31], v[22:23]
	v_cvt_f32_u32_e32 v160, v160
	v_cvt_f32_u32_e32 v161, v161
	v_fmamk_f32 v160, v161, 0x4f800000, v160
	v_fmamk_f32 v20, v160, 0x26800000, v192
	v_mov_b32_e32 v246, v20
	v_cvt_pk_bf16_f32 v17, v22, v23
	v_rsq_f32_e32 v22, v20
	v_mad_i64_i32 v[20:21], s[46:47], v158, s61, v[112:113]
	v_lshl_add_u64 v[20:21], v[20:21], 0, v[114:115]
	v_cvt_pk_bf16_f32 v18, v24, v25
	v_cvt_pk_bf16_f32 v19, v26, v27
	global_store_dwordx4 v[20:21], v[16:19], off
	v_pk_mul_f32 v[12:13], v[12:13], v[4:5]
	v_pk_mul_f32 v[8:9], v[8:9], v[0:1]
	v_mul_f32_e32 v16, 0xbfb8aa3b, v22
	v_pk_mul_f32 v[4:5], v[4:5], v[16:17] op_sel_hi:[1,0]
	v_pk_mul_f32 v[0:1], v[0:1], v[16:17] op_sel_hi:[1,0]
	v_exp_f32_e32 v4, v4
	v_exp_f32_e32 v5, v5
	v_pk_mul_f32 v[10:11], v[10:11], v[2:3]
	v_exp_f32_e32 v0, v0
	v_exp_f32_e32 v1, v1
	v_pk_mul_f32 v[2:3], v[2:3], v[16:17] op_sel_hi:[1,0]
	v_pk_mul_f32 v[14:15], v[14:15], v[6:7]
	v_exp_f32_e32 v2, v2
	v_exp_f32_e32 v3, v3
	v_pk_mul_f32 v[6:7], v[6:7], v[16:17] op_sel_hi:[1,0]
	v_pk_fma_f32 v[4:5], v[4:5], v[246:247], v[246:247] op_sel_hi:[1,0,0]
	v_exp_f32_e32 v6, v6
	v_exp_f32_e32 v7, v7
	v_pk_fma_f32 v[0:1], v[0:1], v[246:247], v[246:247] op_sel_hi:[1,0,0]
	v_rcp_f32_e32 v4, v4
	v_rcp_f32_e32 v5, v5
	v_rcp_f32_e32 v0, v0
	v_rcp_f32_e32 v1, v1
	v_pk_fma_f32 v[2:3], v[2:3], v[246:247], v[246:247] op_sel_hi:[1,0,0]
	v_rcp_f32_e32 v2, v2
	v_rcp_f32_e32 v3, v3
	v_pk_fma_f32 v[6:7], v[6:7], v[246:247], v[246:247] op_sel_hi:[1,0,0]
	v_rcp_f32_e32 v6, v6
	v_rcp_f32_e32 v7, v7
	v_pk_mul_f32 v[4:5], v[12:13], v[4:5]
	v_pk_mul_f32 v[8:9], v[8:9], v[0:1]
	v_pk_mul_f32 v[10:11], v[10:11], v[2:3]
	v_cvt_pk_bf16_f32 v0, v4, v5
	v_mad_i64_i32 v[4:5], s[46:47], v140, s61, v[112:113]
	v_lshl_add_u64 v[4:5], v[4:5], 0, v[114:115]
	s_and_b64 vcc, exec, s[2:3]
	s_mov_b64 s[2:3], -1
	v_pk_mul_f32 v[6:7], v[14:15], v[6:7]
	s_nop 0
	v_cvt_pk_bf16_f32 v1, v6, v7
	v_cvt_pk_bf16_f32 v2, v8, v9
	v_cvt_pk_bf16_f32 v3, v10, v11
	global_store_dwordx4 v[4:5], v[0:3], off
	s_cbranch_vccnz .LBB0_1289
	s_nop 0
	v_or_b32_e32 v0, v157, v155
	v_or_b32_e32 v1, v156, v154
	v_or3_b32 v0, v0, v151, v153
	v_or3_b32 v1, v1, v150, v152
	v_or3_b32 v0, v0, v147, v149
	v_or3_b32 v1, v1, v146, v148
	s_andn2_b64 vcc, exec, s[4:5]
	v_or3_b32 v0, v0, v143, v145
	v_or3_b32 v1, v1, v142, v144
	s_cbranch_vccnz .LBB0_1288
	s_barrier
	s_branch .LBB0_1288
